# gather u-sweep dot products as bf16 dot2 (table bytes fp8->bf16 pairs by v_cvt_scalef32_pk_bf16_fp8, x slice as bf16 pairs, f32 accumulate) -- the numeric path the baseline uses for these dots
# speedup vs baseline: 1.0125x; 1.0045x over previous
; DEVI float4 ldbf4(const uint16_t* p) { const uint2 v = *(const uint2*)p; return make_float4(bflo(v.x), bfhi(v.x), bflo(v.y), bfhi(v.y)); }
; __device__ void phase_gather(const P& p, int vb, int nvb, char* smem) {
;     ...
;   for (int base = (vb * 4 + wave) * 4; base < NREAL; base += nvb * 16) {
;     const int rr = base + g;
;     const uint16_t* hr = h2 + (size_t)rr * DM;
;     f32x2 xf[32];
;     {
;       float ss = 0.f;
; #pragma unroll
;       for (int i = 0; i < 4; i++)
; #pragma unroll
;         for (int q = 0; q < 4; q++) {
;           const float4 a = ldbf4(hr + i * 256 + 16 * j + 4 * q);
;           ss += a.x * a.x + a.y * a.y + a.z * a.z + a.w * a.w;
;         }
;       const float rstd = rsqrtf(wsum16(ss) * (1.f / 1024.f) + EPS);
.LBB0_496:
	v_or_b32_e32 v0, v126, v127
	v_ashrrev_i32_e32 v1, 31, v0
	v_lshlrev_b64 v[2:3], 11, v[0:1]
	v_lshl_add_u64 v[28:29], v[24:25], 0, v[2:3]
	global_load_dwordx4 v[2:5], v[28:29], off
	global_load_dwordx4 v[6:9], v[28:29], off offset:16
	global_load_dwordx4 v[30:33], v[28:29], off offset:512
	global_load_dwordx4 v[34:37], v[28:29], off offset:528
	global_load_dwordx4 v[38:41], v[28:29], off offset:1024
	global_load_dwordx4 v[42:45], v[28:29], off offset:1040
	global_load_dwordx4 v[46:49], v[28:29], off offset:1536
	global_load_dwordx4 v[50:53], v[28:29], off offset:1552
	s_waitcnt vmcnt(7)
	v_lshlrev_b32_e32 v58, 16, v4
	v_and_b32_e32 v59, 0xffff0000, v4
	v_lshlrev_b32_e32 v60, 16, v5
	v_and_b32_e32 v61, 0xffff0000, v5
	s_waitcnt vmcnt(6)
	v_lshlrev_b32_e32 v62, 16, v6
	v_and_b32_e32 v63, 0xffff0000, v6
	v_lshlrev_b32_e32 v64, 16, v7
	v_and_b32_e32 v65, 0xffff0000, v7
	v_lshlrev_b32_e32 v6, 16, v8
	v_and_b32_e32 v7, 0xffff0000, v8
	v_lshlrev_b32_e32 v4, 16, v9
	v_and_b32_e32 v5, 0xffff0000, v9
	s_waitcnt vmcnt(2)
	v_and_b32_e32 v9, 0xffff0000, v44
	v_and_b32_e32 v8, 0xffff0000, v42
	v_lshlrev_b32_e32 v54, 16, v2
	v_and_b32_e32 v55, 0xffff0000, v2
	v_lshlrev_b32_e32 v56, 16, v3
	v_and_b32_e32 v57, 0xffff0000, v3
	v_lshlrev_b32_e32 v3, 16, v44
	v_lshlrev_b32_e32 v2, 16, v42
	v_pk_mul_f32 v[8:9], v[8:9], v[8:9]
	v_lshlrev_b32_e32 v69, 16, v32
	v_and_b32_e32 v32, 0xffff0000, v32
	v_lshlrev_b32_e32 v72, 16, v34
	v_and_b32_e32 v34, 0xffff0000, v34
	v_pk_fma_f32 v[2:3], v[2:3], v[2:3], v[8:9]
	s_waitcnt vmcnt(1)
	v_and_b32_e32 v9, 0xffff0000, v48
	v_and_b32_e32 v8, 0xffff0000, v46
	v_lshlrev_b32_e32 v70, 16, v33
	v_and_b32_e32 v71, 0xffff0000, v33
	v_lshlrev_b32_e32 v11, 16, v45
	v_lshlrev_b32_e32 v10, 16, v43
	v_lshlrev_b32_e32 v33, 16, v48
	v_mul_f32_e32 v81, v32, v32
	v_mul_f32_e32 v82, v34, v34
	v_lshlrev_b32_e32 v32, 16, v46
	v_pk_mul_f32 v[8:9], v[8:9], v[8:9]
	v_lshlrev_b32_e32 v12, 16, v30
	v_and_b32_e32 v66, 0xffff0000, v30
	v_lshlrev_b32_e32 v67, 16, v31
	v_and_b32_e32 v68, 0xffff0000, v31
	v_lshlrev_b32_e32 v73, 16, v35
	v_and_b32_e32 v31, 0xffff0000, v45
	v_and_b32_e32 v30, 0xffff0000, v43
	v_fmac_f32_e32 v82, v72, v72
	v_pk_fma_f32 v[2:3], v[10:11], v[10:11], v[2:3]
	v_lshlrev_b32_e32 v11, 16, v49
	v_lshlrev_b32_e32 v10, 16, v47
	v_pk_fma_f32 v[8:9], v[32:33], v[32:33], v[8:9]
	v_and_b32_e32 v35, 0xffff0000, v35
	v_fmac_f32_e32 v82, v73, v73
	v_pk_fma_f32 v[2:3], v[30:31], v[30:31], v[2:3]
	v_and_b32_e32 v31, 0xffff0000, v49
	v_and_b32_e32 v30, 0xffff0000, v47
	v_pk_fma_f32 v[8:9], v[10:11], v[10:11], v[8:9]
	v_fmac_f32_e32 v82, v35, v35
	v_pk_fma_f32 v[30:31], v[30:31], v[30:31], v[8:9]
	global_load_dwordx4 v[8:11], v[14:15], off offset:16
	global_load_dwordx4 v[32:35], v[14:15], off
	v_lshlrev_b32_e32 v76, 16, v38
	v_and_b32_e32 v38, 0xffff0000, v38
	v_lshlrev_b32_e32 v74, 16, v36
	v_and_b32_e32 v36, 0xffff0000, v36
	v_mul_f32_e32 v84, v38, v38
	v_lshlrev_b32_e32 v77, 16, v39
	v_lshlrev_b32_e32 v78, 16, v40
	v_and_b32_e32 v40, 0xffff0000, v40
	v_mul_f32_e32 v83, v36, v36
	v_fmac_f32_e32 v84, v76, v76
	v_lshlrev_b32_e32 v75, 16, v37
	v_and_b32_e32 v39, 0xffff0000, v39
	v_mul_f32_e32 v85, v40, v40
	v_fmac_f32_e32 v83, v74, v74
	v_fmac_f32_e32 v84, v77, v77
	v_and_b32_e32 v37, 0xffff0000, v37
	v_lshlrev_b32_e32 v79, 16, v41
	v_fmac_f32_e32 v85, v78, v78
	v_fmac_f32_e32 v83, v75, v75
	v_fmac_f32_e32 v84, v39, v39
	s_waitcnt vmcnt(2)
	v_and_b32_e32 v39, 0xffff0000, v52
	v_and_b32_e32 v38, 0xffff0000, v50
	v_and_b32_e32 v41, 0xffff0000, v41
	v_fmac_f32_e32 v85, v79, v79
	v_fmac_f32_e32 v83, v37, v37
	v_lshlrev_b32_e32 v37, 16, v52
	v_lshlrev_b32_e32 v36, 16, v50
	v_pk_mul_f32 v[38:39], v[38:39], v[38:39]
	v_fmac_f32_e32 v85, v41, v41
	v_lshlrev_b32_e32 v41, 16, v53
	v_lshlrev_b32_e32 v40, 16, v51
	v_pk_fma_f32 v[36:37], v[36:37], v[36:37], v[38:39]
	v_and_b32_e32 v43, 0xffff0000, v53
	v_and_b32_e32 v42, 0xffff0000, v51
	v_pk_fma_f32 v[36:37], v[40:41], v[40:41], v[36:37]
	v_mul_f32_e32 v80, v66, v66
	v_pk_fma_f32 v[36:37], v[42:43], v[42:43], v[36:37]
	global_load_dwordx4 v[40:43], v[14:15], off offset:32
	v_fmac_f32_e32 v80, v12, v12
	v_fmac_f32_e32 v80, v67, v67
	v_pk_mul_f32 v[52:53], v[58:59], v[58:59]
	v_fmac_f32_e32 v81, v69, v69
	v_fmac_f32_e32 v80, v68, v68
	v_pk_mul_f32 v[50:51], v[60:61], v[60:61]
	v_pk_mul_f32 v[68:69], v[54:55], v[54:55]
	v_add_f32_e32 v12, v52, v53
	v_pk_mul_f32 v[48:49], v[62:63], v[62:63]
	v_pk_mul_f32 v[66:67], v[56:57], v[56:57]
	v_add_f32_e32 v12, v12, v50
	v_add_f32_e32 v50, v68, v69
	v_pk_mul_f32 v[46:47], v[64:65], v[64:65]
	v_add_f32_e32 v50, v50, v66
	v_add_f32_e32 v48, v48, v49
	v_pk_mul_f32 v[44:45], v[6:7], v[6:7]
	v_add_f32_e32 v12, v51, v12
	v_add_f32_e32 v50, v67, v50
	v_add_f32_e32 v46, v48, v46
	v_pk_mul_f32 v[38:39], v[4:5], v[4:5]
	v_add_f32_e32 v12, v50, v12
	v_add_f32_e32 v46, v47, v46
	v_add_f32_e32 v44, v44, v45
	v_add_f32_e32 v12, v12, v46
	v_add_f32_e32 v38, v44, v38
	global_load_dwordx4 v[44:47], v[14:15], off offset:48
	v_add_f32_e32 v38, v39, v38
	v_fmac_f32_e32 v81, v70, v70
	v_add_f32_e32 v12, v12, v38
	v_fmac_f32_e32 v81, v71, v71
	v_add_f32_e32 v12, v12, v80
	v_add_f32_e32 v12, v12, v81
	v_add_f32_e32 v12, v12, v82
	v_add_f32_e32 v12, v12, v83
	v_add_f32_e32 v12, v12, v84
	v_add_f32_e32 v12, v12, v85
	v_add_f32_e32 v2, v12, v2
	v_add_f32_e32 v2, v2, v3
	v_add_f32_e32 v2, v2, v30
	v_add_f32_e32 v2, v2, v31
	v_add_f32_e32 v2, v2, v36
	v_add_f32_e32 v2, v2, v37
	ds_bpermute_b32 v3, v128, v2
	v_lshlrev_b64 v[30:31], 10, v[0:1]
	s_waitcnt lgkmcnt(0)
	v_add_f32_e32 v2, v2, v3
	ds_bpermute_b32 v3, v129, v2
	s_waitcnt lgkmcnt(0)
	v_add_f32_e32 v2, v2, v3
	ds_bpermute_b32 v3, v130, v2
	s_waitcnt lgkmcnt(0)
; DEVI uint32_t f2bf(float f) { uint32_t u = __float_as_uint(f); return (u + 0x7fffu + ((u >> 16) & 1u)) >> 16; }
; DEVI float bf1(uint16_t h) { return __uint_as_float(((uint32_t)h) << 16); }
; DEVI float4 ldbf4(const uint16_t* p) { const uint2 v = *(const uint2*)p; return make_float4(bflo(v.x), bfhi(v.x), bflo(v.y), bfhi(v.y)); }
; __device__ void phase_gather(const P& p, int vb, int nvb, char* smem) {
;     ...
;       const float rstd = rsqrtf(wsum16(ss) * (1.f / 1024.f) + EPS);
; #pragma unroll
;       for (int i = 0; i < 4; i++) {
; #pragma unroll
;         for (int q = 0; q < 4; q++) {
;           const float4 a = ldbf4(hr + i * 256 + 16 * j + 4 * q);
;           const float4 ga = *(const float4*)(gf + i * 256 + 16 * j + 4 * q);
;           xf[i * 8 + q * 2 + 0] = f32x2{bf1((uint16_t)f2bf(a.x * rstd * ga.x)), bf1((uint16_t)f2bf(a.y * rstd * ga.y))};
;           xf[i * 8 + q * 2 + 1] = f32x2{bf1((uint16_t)f2bf(a.z * rstd * ga.z)), bf1((uint16_t)f2bf(a.w * rstd * ga.w))};
;         }
;         __builtin_amdgcn_sched_barrier(0);
;       }
	v_add_f32_e32 v2, v2, v3
	ds_bpermute_b32 v3, v131, v2
	s_waitcnt lgkmcnt(0)
	v_add_f32_e32 v2, v2, v3
	v_fmamk_f32 v2, v2, 0x3a800000, v143
	v_mul_f32_e32 v3, 0x4b800000, v2
	v_cmp_gt_f32_e64 s[20:21], s29, v2
	s_nop 1
	v_cndmask_b32_e64 v2, v2, v3, s[20:21]
	v_rsq_f32_e32 v2, v2
	s_nop 0
	v_mul_f32_e32 v3, 0x45800000, v2
	v_cndmask_b32_e64 v2, v2, v3, s[20:21]
	v_pk_mul_f32 v[36:37], v[2:3], v[54:55] op_sel_hi:[0,1]
	s_waitcnt vmcnt(2)
	v_pk_mul_f32 v[32:33], v[32:33], v[36:37]
	s_nop 0
	v_and_b32_sdwa v3, v33, v146 dst_sel:DWORD dst_unused:UNUSED_PAD src0_sel:WORD_1 src1_sel:DWORD
	v_add3_u32 v3, v33, v3, s30
	v_pk_mul_f32 v[36:37], v[2:3], v[56:57] op_sel_hi:[0,1]
	v_pk_mul_f32 v[34:35], v[34:35], v[36:37]
	v_and_b32_sdwa v12, v32, v146 dst_sel:DWORD dst_unused:UNUSED_PAD src0_sel:WORD_1 src1_sel:DWORD
	v_and_b32_e32 v33, 0xffff0000, v3
	v_and_b32_sdwa v3, v35, v146 dst_sel:DWORD dst_unused:UNUSED_PAD src0_sel:WORD_1 src1_sel:DWORD
	v_add3_u32 v12, v32, v12, s30
	v_add3_u32 v3, v35, v3, s30
	v_and_b32_e32 v32, 0xffff0000, v12
	v_and_b32_sdwa v12, v34, v146 dst_sel:DWORD dst_unused:UNUSED_PAD src0_sel:WORD_1 src1_sel:DWORD
	v_pk_mul_f32 v[36:37], v[2:3], v[58:59] op_sel_hi:[0,1]
	v_add3_u32 v12, v34, v12, s30
	v_pk_mul_f32 v[8:9], v[8:9], v[36:37]
	v_and_b32_e32 v35, 0xffff0000, v3
	v_and_b32_e32 v34, 0xffff0000, v12
	v_and_b32_sdwa v3, v9, v146 dst_sel:DWORD dst_unused:UNUSED_PAD src0_sel:WORD_1 src1_sel:DWORD
	v_and_b32_sdwa v12, v8, v146 dst_sel:DWORD dst_unused:UNUSED_PAD src0_sel:WORD_1 src1_sel:DWORD
	v_add3_u32 v3, v9, v3, s30
	v_add3_u32 v8, v8, v12, s30
	v_and_b32_e32 v36, 0xffff0000, v8
	v_pk_mul_f32 v[8:9], v[2:3], v[60:61] op_sel_hi:[0,1]
	v_pk_mul_f32 v[8:9], v[10:11], v[8:9]
	v_and_b32_e32 v37, 0xffff0000, v3
	v_and_b32_sdwa v3, v9, v146 dst_sel:DWORD dst_unused:UNUSED_PAD src0_sel:WORD_1 src1_sel:DWORD
	v_and_b32_sdwa v10, v8, v146 dst_sel:DWORD dst_unused:UNUSED_PAD src0_sel:WORD_1 src1_sel:DWORD
	v_add3_u32 v3, v9, v3, s30
	v_add3_u32 v8, v8, v10, s30
	v_and_b32_e32 v38, 0xffff0000, v8
	v_pk_mul_f32 v[8:9], v[2:3], v[62:63] op_sel_hi:[0,1]
	s_waitcnt vmcnt(1)
	v_pk_mul_f32 v[8:9], v[40:41], v[8:9]
	v_and_b32_e32 v39, 0xffff0000, v3
	v_and_b32_sdwa v3, v9, v146 dst_sel:DWORD dst_unused:UNUSED_PAD src0_sel:WORD_1 src1_sel:DWORD
	v_and_b32_sdwa v10, v8, v146 dst_sel:DWORD dst_unused:UNUSED_PAD src0_sel:WORD_1 src1_sel:DWORD
	v_add3_u32 v3, v9, v3, s30
	v_add3_u32 v8, v8, v10, s30
	v_and_b32_e32 v40, 0xffff0000, v8
	v_pk_mul_f32 v[8:9], v[2:3], v[64:65] op_sel_hi:[0,1]
	v_pk_mul_f32 v[8:9], v[42:43], v[8:9]
	v_and_b32_e32 v41, 0xffff0000, v3
	v_and_b32_sdwa v3, v9, v146 dst_sel:DWORD dst_unused:UNUSED_PAD src0_sel:WORD_1 src1_sel:DWORD
	v_add3_u32 v3, v9, v3, s30
	v_pk_mul_f32 v[6:7], v[2:3], v[6:7] op_sel_hi:[0,1]
	s_waitcnt vmcnt(0)
	v_pk_mul_f32 v[6:7], v[44:45], v[6:7]
	v_and_b32_sdwa v10, v8, v146 dst_sel:DWORD dst_unused:UNUSED_PAD src0_sel:WORD_1 src1_sel:DWORD
	v_and_b32_e32 v43, 0xffff0000, v3
	v_and_b32_sdwa v3, v7, v146 dst_sel:DWORD dst_unused:UNUSED_PAD src0_sel:WORD_1 src1_sel:DWORD
	v_add3_u32 v8, v8, v10, s30
	v_add3_u32 v3, v7, v3, s30
	v_and_b32_e32 v42, 0xffff0000, v8
	v_and_b32_sdwa v8, v6, v146 dst_sel:DWORD dst_unused:UNUSED_PAD src0_sel:WORD_1 src1_sel:DWORD
	v_pk_mul_f32 v[4:5], v[2:3], v[4:5] op_sel_hi:[0,1]
	v_add3_u32 v6, v6, v8, s30
	v_pk_mul_f32 v[4:5], v[4:5], v[46:47]
	v_and_b32_e32 v45, 0xffff0000, v3
	v_and_b32_e32 v44, 0xffff0000, v6
	v_and_b32_sdwa v3, v5, v146 dst_sel:DWORD dst_unused:UNUSED_PAD src0_sel:WORD_1 src1_sel:DWORD
	v_and_b32_sdwa v6, v4, v146 dst_sel:DWORD dst_unused:UNUSED_PAD src0_sel:WORD_1 src1_sel:DWORD
	v_add3_u32 v3, v5, v3, s30
	v_add3_u32 v4, v4, v6, s30
	v_and_b32_e32 v47, 0xffff0000, v3
	v_and_b32_e32 v46, 0xffff0000, v4
	global_load_dwordx4 v[4:7], v[28:29], off offset:512
	global_load_dwordx4 v[8:11], v[28:29], off offset:528
	global_load_dwordx4 v[48:51], v[14:15], off offset:1024
	global_load_dwordx4 v[52:55], v[14:15], off offset:1040
	global_load_dwordx4 v[56:59], v[14:15], off offset:1056
	global_load_dwordx4 v[60:63], v[14:15], off offset:1072
	s_waitcnt vmcnt(5)
	v_lshlrev_b32_e32 v64, 16, v4
	v_and_b32_e32 v65, 0xffff0000, v4
	v_lshlrev_b32_e32 v4, 16, v5
	v_and_b32_e32 v5, 0xffff0000, v5
	v_lshlrev_b32_e32 v66, 16, v6
	v_and_b32_e32 v67, 0xffff0000, v6
	v_lshlrev_b32_e32 v6, 16, v7
	v_and_b32_e32 v7, 0xffff0000, v7
	s_waitcnt vmcnt(4)
	v_lshlrev_b32_e32 v68, 16, v8
	v_and_b32_e32 v69, 0xffff0000, v8
	v_lshlrev_b32_e32 v8, 16, v9
	v_and_b32_e32 v9, 0xffff0000, v9
	v_lshlrev_b32_e32 v70, 16, v10
	v_and_b32_e32 v71, 0xffff0000, v10
	v_lshlrev_b32_e32 v10, 16, v11
	v_and_b32_e32 v11, 0xffff0000, v11
	v_pk_mul_f32 v[64:65], v[2:3], v[64:65] op_sel_hi:[0,1]
	v_pk_mul_f32 v[4:5], v[2:3], v[4:5] op_sel_hi:[0,1]
	v_pk_mul_f32 v[66:67], v[2:3], v[66:67] op_sel_hi:[0,1]
	v_pk_mul_f32 v[6:7], v[2:3], v[6:7] op_sel_hi:[0,1]
	v_pk_mul_f32 v[68:69], v[2:3], v[68:69] op_sel_hi:[0,1]
	v_pk_mul_f32 v[8:9], v[2:3], v[8:9] op_sel_hi:[0,1]
	v_pk_mul_f32 v[70:71], v[2:3], v[70:71] op_sel_hi:[0,1]
	v_pk_mul_f32 v[10:11], v[2:3], v[10:11] op_sel_hi:[0,1]
	s_waitcnt vmcnt(3)
	v_pk_mul_f32 v[48:49], v[48:49], v[64:65]
	v_pk_mul_f32 v[4:5], v[4:5], v[50:51]
	s_waitcnt vmcnt(2)
	v_pk_mul_f32 v[50:51], v[52:53], v[66:67]
	v_pk_mul_f32 v[6:7], v[6:7], v[54:55]
	s_waitcnt vmcnt(1)
	v_pk_mul_f32 v[52:53], v[56:57], v[68:69]
	v_pk_mul_f32 v[8:9], v[8:9], v[58:59]
	s_waitcnt vmcnt(0)
; DEVI uint32_t f2bf(float f) { uint32_t u = __float_as_uint(f); return (u + 0x7fffu + ((u >> 16) & 1u)) >> 16; }
; DEVI float bf1(uint16_t h) { return __uint_as_float(((uint32_t)h) << 16); }
; DEVI float4 ldbf4(const uint16_t* p) { const uint2 v = *(const uint2*)p; return make_float4(bflo(v.x), bfhi(v.x), bflo(v.y), bfhi(v.y)); }
; __device__ void phase_gather(const P& p, int vb, int nvb, char* smem) {
;     ...
; #pragma unroll
;       for (int i = 0; i < 4; i++) {
; #pragma unroll
;         for (int q = 0; q < 4; q++) {
;           const float4 a = ldbf4(hr + i * 256 + 16 * j + 4 * q);
;           const float4 ga = *(const float4*)(gf + i * 256 + 16 * j + 4 * q);
;           xf[i * 8 + q * 2 + 0] = f32x2{bf1((uint16_t)f2bf(a.x * rstd * ga.x)), bf1((uint16_t)f2bf(a.y * rstd * ga.y))};
;           xf[i * 8 + q * 2 + 1] = f32x2{bf1((uint16_t)f2bf(a.z * rstd * ga.z)), bf1((uint16_t)f2bf(a.w * rstd * ga.w))};
;         }
;         __builtin_amdgcn_sched_barrier(0);
;       }
	v_pk_mul_f32 v[54:55], v[60:61], v[70:71]
	v_pk_mul_f32 v[10:11], v[10:11], v[62:63]
	v_and_b32_sdwa v3, v49, v146 dst_sel:DWORD dst_unused:UNUSED_PAD src0_sel:WORD_1 src1_sel:DWORD
	v_and_b32_sdwa v12, v48, v146 dst_sel:DWORD dst_unused:UNUSED_PAD src0_sel:WORD_1 src1_sel:DWORD
	v_and_b32_sdwa v56, v5, v146 dst_sel:DWORD dst_unused:UNUSED_PAD src0_sel:WORD_1 src1_sel:DWORD
	v_and_b32_sdwa v57, v4, v146 dst_sel:DWORD dst_unused:UNUSED_PAD src0_sel:WORD_1 src1_sel:DWORD
	v_and_b32_sdwa v58, v51, v146 dst_sel:DWORD dst_unused:UNUSED_PAD src0_sel:WORD_1 src1_sel:DWORD
	v_and_b32_sdwa v59, v50, v146 dst_sel:DWORD dst_unused:UNUSED_PAD src0_sel:WORD_1 src1_sel:DWORD
	v_and_b32_sdwa v60, v7, v146 dst_sel:DWORD dst_unused:UNUSED_PAD src0_sel:WORD_1 src1_sel:DWORD
	v_and_b32_sdwa v61, v6, v146 dst_sel:DWORD dst_unused:UNUSED_PAD src0_sel:WORD_1 src1_sel:DWORD
	v_and_b32_sdwa v62, v53, v146 dst_sel:DWORD dst_unused:UNUSED_PAD src0_sel:WORD_1 src1_sel:DWORD
	v_and_b32_sdwa v63, v52, v146 dst_sel:DWORD dst_unused:UNUSED_PAD src0_sel:WORD_1 src1_sel:DWORD
	v_and_b32_sdwa v64, v9, v146 dst_sel:DWORD dst_unused:UNUSED_PAD src0_sel:WORD_1 src1_sel:DWORD
	v_and_b32_sdwa v65, v8, v146 dst_sel:DWORD dst_unused:UNUSED_PAD src0_sel:WORD_1 src1_sel:DWORD
	v_and_b32_sdwa v66, v55, v146 dst_sel:DWORD dst_unused:UNUSED_PAD src0_sel:WORD_1 src1_sel:DWORD
	v_and_b32_sdwa v67, v54, v146 dst_sel:DWORD dst_unused:UNUSED_PAD src0_sel:WORD_1 src1_sel:DWORD
	v_and_b32_sdwa v68, v11, v146 dst_sel:DWORD dst_unused:UNUSED_PAD src0_sel:WORD_1 src1_sel:DWORD
	v_and_b32_sdwa v69, v10, v146 dst_sel:DWORD dst_unused:UNUSED_PAD src0_sel:WORD_1 src1_sel:DWORD
	v_add3_u32 v3, v49, v3, s30
	v_add3_u32 v12, v48, v12, s30
	v_add3_u32 v5, v5, v56, s30
	v_add3_u32 v4, v4, v57, s30
	v_add3_u32 v56, v51, v58, s30
	v_add3_u32 v57, v50, v59, s30
	v_add3_u32 v7, v7, v60, s30
	v_add3_u32 v6, v6, v61, s30
	v_add3_u32 v58, v53, v62, s30
	v_add3_u32 v59, v52, v63, s30
	v_add3_u32 v9, v9, v64, s30
	v_add3_u32 v8, v8, v65, s30
	v_add3_u32 v60, v55, v66, s30
	v_add3_u32 v62, v54, v67, s30
	v_add3_u32 v11, v11, v68, s30
	v_add3_u32 v10, v10, v69, s30
	v_and_b32_e32 v49, 0xffff0000, v3
	v_and_b32_e32 v48, 0xffff0000, v12
	v_and_b32_e32 v51, 0xffff0000, v5
	v_and_b32_e32 v50, 0xffff0000, v4
	v_and_b32_e32 v53, 0xffff0000, v56
	v_and_b32_e32 v52, 0xffff0000, v57
	v_and_b32_e32 v55, 0xffff0000, v7
	v_and_b32_e32 v54, 0xffff0000, v6
	v_and_b32_e32 v57, 0xffff0000, v58
	v_and_b32_e32 v56, 0xffff0000, v59
	v_and_b32_e32 v59, 0xffff0000, v9
	v_and_b32_e32 v58, 0xffff0000, v8
	v_and_b32_e32 v61, 0xffff0000, v60
	v_and_b32_e32 v60, 0xffff0000, v62
	v_and_b32_e32 v63, 0xffff0000, v11
	v_and_b32_e32 v62, 0xffff0000, v10
	global_load_dwordx4 v[4:7], v[28:29], off offset:1024
	global_load_dwordx4 v[8:11], v[28:29], off offset:1040
	global_load_dwordx4 v[64:67], v[14:15], off offset:2048
	global_load_dwordx4 v[68:71], v[14:15], off offset:2064
	global_load_dwordx4 v[72:75], v[14:15], off offset:2080
	global_load_dwordx4 v[76:79], v[14:15], off offset:2096
	s_waitcnt vmcnt(5)
	v_lshlrev_b32_e32 v80, 16, v4
	v_and_b32_e32 v81, 0xffff0000, v4
	v_lshlrev_b32_e32 v4, 16, v5
	v_and_b32_e32 v5, 0xffff0000, v5
	v_lshlrev_b32_e32 v82, 16, v6
	v_and_b32_e32 v83, 0xffff0000, v6
	v_lshlrev_b32_e32 v6, 16, v7
	v_and_b32_e32 v7, 0xffff0000, v7
	s_waitcnt vmcnt(4)
	v_lshlrev_b32_e32 v84, 16, v8
	v_and_b32_e32 v85, 0xffff0000, v8
	v_lshlrev_b32_e32 v8, 16, v9
	v_and_b32_e32 v9, 0xffff0000, v9
	v_lshlrev_b32_e32 v86, 16, v10
	v_and_b32_e32 v87, 0xffff0000, v10
	v_lshlrev_b32_e32 v10, 16, v11
	v_and_b32_e32 v11, 0xffff0000, v11
	v_pk_mul_f32 v[80:81], v[2:3], v[80:81] op_sel_hi:[0,1]
	v_pk_mul_f32 v[4:5], v[2:3], v[4:5] op_sel_hi:[0,1]
	v_pk_mul_f32 v[82:83], v[2:3], v[82:83] op_sel_hi:[0,1]
	v_pk_mul_f32 v[6:7], v[2:3], v[6:7] op_sel_hi:[0,1]
	v_pk_mul_f32 v[84:85], v[2:3], v[84:85] op_sel_hi:[0,1]
	v_pk_mul_f32 v[8:9], v[2:3], v[8:9] op_sel_hi:[0,1]
	v_pk_mul_f32 v[86:87], v[2:3], v[86:87] op_sel_hi:[0,1]
	v_pk_mul_f32 v[10:11], v[2:3], v[10:11] op_sel_hi:[0,1]
	s_waitcnt vmcnt(3)
	v_pk_mul_f32 v[64:65], v[64:65], v[80:81]
	v_pk_mul_f32 v[4:5], v[4:5], v[66:67]
	s_waitcnt vmcnt(2)
	v_pk_mul_f32 v[66:67], v[68:69], v[82:83]
	v_pk_mul_f32 v[6:7], v[6:7], v[70:71]
	s_waitcnt vmcnt(1)
	v_pk_mul_f32 v[68:69], v[72:73], v[84:85]
	v_pk_mul_f32 v[8:9], v[8:9], v[74:75]
	s_waitcnt vmcnt(0)
; DEVI uint32_t f2bf(float f) { uint32_t u = __float_as_uint(f); return (u + 0x7fffu + ((u >> 16) & 1u)) >> 16; }
; DEVI float bf1(uint16_t h) { return __uint_as_float(((uint32_t)h) << 16); }
; DEVI float4 ldbf4(const uint16_t* p) { const uint2 v = *(const uint2*)p; return make_float4(bflo(v.x), bfhi(v.x), bflo(v.y), bfhi(v.y)); }
; __device__ void phase_gather(const P& p, int vb, int nvb, char* smem) {
;     ...
; #pragma unroll
;       for (int i = 0; i < 4; i++) {
; #pragma unroll
;         for (int q = 0; q < 4; q++) {
;           const float4 a = ldbf4(hr + i * 256 + 16 * j + 4 * q);
;           const float4 ga = *(const float4*)(gf + i * 256 + 16 * j + 4 * q);
;           xf[i * 8 + q * 2 + 0] = f32x2{bf1((uint16_t)f2bf(a.x * rstd * ga.x)), bf1((uint16_t)f2bf(a.y * rstd * ga.y))};
;           xf[i * 8 + q * 2 + 1] = f32x2{bf1((uint16_t)f2bf(a.z * rstd * ga.z)), bf1((uint16_t)f2bf(a.w * rstd * ga.w))};
;         }
;         __builtin_amdgcn_sched_barrier(0);
;       }
	v_pk_mul_f32 v[70:71], v[76:77], v[86:87]
	v_pk_mul_f32 v[10:11], v[10:11], v[78:79]
	v_and_b32_sdwa v3, v65, v146 dst_sel:DWORD dst_unused:UNUSED_PAD src0_sel:WORD_1 src1_sel:DWORD
	v_and_b32_sdwa v12, v64, v146 dst_sel:DWORD dst_unused:UNUSED_PAD src0_sel:WORD_1 src1_sel:DWORD
	v_and_b32_sdwa v72, v5, v146 dst_sel:DWORD dst_unused:UNUSED_PAD src0_sel:WORD_1 src1_sel:DWORD
	v_and_b32_sdwa v73, v4, v146 dst_sel:DWORD dst_unused:UNUSED_PAD src0_sel:WORD_1 src1_sel:DWORD
	v_and_b32_sdwa v74, v67, v146 dst_sel:DWORD dst_unused:UNUSED_PAD src0_sel:WORD_1 src1_sel:DWORD
	v_and_b32_sdwa v75, v66, v146 dst_sel:DWORD dst_unused:UNUSED_PAD src0_sel:WORD_1 src1_sel:DWORD
	v_and_b32_sdwa v76, v7, v146 dst_sel:DWORD dst_unused:UNUSED_PAD src0_sel:WORD_1 src1_sel:DWORD
	v_and_b32_sdwa v77, v6, v146 dst_sel:DWORD dst_unused:UNUSED_PAD src0_sel:WORD_1 src1_sel:DWORD
	v_and_b32_sdwa v78, v69, v146 dst_sel:DWORD dst_unused:UNUSED_PAD src0_sel:WORD_1 src1_sel:DWORD
	v_and_b32_sdwa v79, v68, v146 dst_sel:DWORD dst_unused:UNUSED_PAD src0_sel:WORD_1 src1_sel:DWORD
	v_and_b32_sdwa v80, v9, v146 dst_sel:DWORD dst_unused:UNUSED_PAD src0_sel:WORD_1 src1_sel:DWORD
	v_and_b32_sdwa v81, v8, v146 dst_sel:DWORD dst_unused:UNUSED_PAD src0_sel:WORD_1 src1_sel:DWORD
	v_and_b32_sdwa v82, v71, v146 dst_sel:DWORD dst_unused:UNUSED_PAD src0_sel:WORD_1 src1_sel:DWORD
	v_and_b32_sdwa v83, v70, v146 dst_sel:DWORD dst_unused:UNUSED_PAD src0_sel:WORD_1 src1_sel:DWORD
	v_and_b32_sdwa v84, v11, v146 dst_sel:DWORD dst_unused:UNUSED_PAD src0_sel:WORD_1 src1_sel:DWORD
	v_and_b32_sdwa v85, v10, v146 dst_sel:DWORD dst_unused:UNUSED_PAD src0_sel:WORD_1 src1_sel:DWORD
	v_add3_u32 v3, v65, v3, s30
	v_add3_u32 v12, v64, v12, s30
	v_add3_u32 v5, v5, v72, s30
	v_add3_u32 v4, v4, v73, s30
	v_add3_u32 v72, v67, v74, s30
	v_add3_u32 v73, v66, v75, s30
	v_add3_u32 v7, v7, v76, s30
	v_add3_u32 v6, v6, v77, s30
	v_add3_u32 v74, v69, v78, s30
	v_add3_u32 v75, v68, v79, s30
	v_add3_u32 v9, v9, v80, s30
	v_add3_u32 v8, v8, v81, s30
	v_add3_u32 v76, v71, v82, s30
	v_add3_u32 v78, v70, v83, s30
	v_add3_u32 v11, v11, v84, s30
	v_add3_u32 v10, v10, v85, s30
	v_and_b32_e32 v65, 0xffff0000, v3
	v_and_b32_e32 v64, 0xffff0000, v12
	v_and_b32_e32 v67, 0xffff0000, v5
	v_and_b32_e32 v66, 0xffff0000, v4
	v_and_b32_e32 v69, 0xffff0000, v72
	v_and_b32_e32 v68, 0xffff0000, v73
	v_and_b32_e32 v71, 0xffff0000, v7
	v_and_b32_e32 v70, 0xffff0000, v6
	v_and_b32_e32 v73, 0xffff0000, v74
	v_and_b32_e32 v72, 0xffff0000, v75
	v_and_b32_e32 v75, 0xffff0000, v9
	v_and_b32_e32 v74, 0xffff0000, v8
	v_and_b32_e32 v77, 0xffff0000, v76
	v_and_b32_e32 v76, 0xffff0000, v78
	v_and_b32_e32 v79, 0xffff0000, v11
	v_and_b32_e32 v78, 0xffff0000, v10
	global_load_dwordx4 v[4:7], v[28:29], off offset:1536
	global_load_dwordx4 v[8:11], v[28:29], off offset:1552
	global_load_dwordx4 v[80:83], v[14:15], off offset:3072
	global_load_dwordx4 v[84:87], v[14:15], off offset:3088
	global_load_dwordx4 v[88:91], v[14:15], off offset:3104
	global_load_dwordx4 v[92:95], v[14:15], off offset:3120
	s_waitcnt vmcnt(5)
	v_lshlrev_b32_e32 v96, 16, v4
	v_and_b32_e32 v97, 0xffff0000, v4
	v_lshlrev_b32_e32 v4, 16, v5
	v_and_b32_e32 v5, 0xffff0000, v5
	v_lshlrev_b32_e32 v98, 16, v6
	v_and_b32_e32 v99, 0xffff0000, v6
	v_lshlrev_b32_e32 v6, 16, v7
	v_and_b32_e32 v7, 0xffff0000, v7
	s_waitcnt vmcnt(4)
	v_lshlrev_b32_e32 v100, 16, v8
	v_and_b32_e32 v101, 0xffff0000, v8
	v_lshlrev_b32_e32 v8, 16, v9
	v_and_b32_e32 v9, 0xffff0000, v9
	v_lshlrev_b32_e32 v102, 16, v10
	v_and_b32_e32 v103, 0xffff0000, v10
	v_lshlrev_b32_e32 v10, 16, v11
	v_and_b32_e32 v11, 0xffff0000, v11
	v_pk_mul_f32 v[96:97], v[2:3], v[96:97] op_sel_hi:[0,1]
	v_pk_mul_f32 v[4:5], v[2:3], v[4:5] op_sel_hi:[0,1]
	v_pk_mul_f32 v[98:99], v[2:3], v[98:99] op_sel_hi:[0,1]
	v_pk_mul_f32 v[6:7], v[2:3], v[6:7] op_sel_hi:[0,1]
	v_pk_mul_f32 v[100:101], v[2:3], v[100:101] op_sel_hi:[0,1]
	v_pk_mul_f32 v[8:9], v[2:3], v[8:9] op_sel_hi:[0,1]
	v_pk_mul_f32 v[102:103], v[2:3], v[102:103] op_sel_hi:[0,1]
	v_pk_mul_f32 v[2:3], v[2:3], v[10:11] op_sel_hi:[0,1]
	s_waitcnt vmcnt(3)
	v_pk_mul_f32 v[10:11], v[80:81], v[96:97]
	v_pk_mul_f32 v[4:5], v[4:5], v[82:83]
	s_waitcnt vmcnt(2)
	v_pk_mul_f32 v[80:81], v[84:85], v[98:99]
	v_pk_mul_f32 v[6:7], v[6:7], v[86:87]
	s_waitcnt vmcnt(1)
	v_pk_mul_f32 v[82:83], v[88:89], v[100:101]
	v_pk_mul_f32 v[8:9], v[8:9], v[90:91]
	s_waitcnt vmcnt(0)
; DEVI uint32_t f2bf(float f) { uint32_t u = __float_as_uint(f); return (u + 0x7fffu + ((u >> 16) & 1u)) >> 16; }
; DEVI float bf1(uint16_t h) { return __uint_as_float(((uint32_t)h) << 16); }
; __device__ void phase_gather(const P& p, int vb, int nvb, char* smem) {
;     ...
;           xf[i * 8 + q * 2 + 0] = f32x2{bf1((uint16_t)f2bf(a.x * rstd * ga.x)), bf1((uint16_t)f2bf(a.y * rstd * ga.y))};
;           xf[i * 8 + q * 2 + 1] = f32x2{bf1((uint16_t)f2bf(a.z * rstd * ga.z)), bf1((uint16_t)f2bf(a.w * rstd * ga.w))};
;     ...
;       uint32_t ks[8];
;       {
;         const int4 a0 = *(const int4*)(seli + (size_t)rr * 128 + j * 8), a1 = *(const int4*)(seli + (size_t)rr * 128 + j * 8 + 4);
;         const int ev[8] = {a0.x, a0.y, a0.z, a0.w, a1.x, a1.y, a1.z, a1.w};
; #pragma unroll
;         for (int r = 0; r < 8; r++) ks[r] = ((uint32_t)ev[r] << 7) | (uint32_t)(j * 8 + r);
;       }
; #pragma unroll
;       for (int k = 2; k <= 128; k <<= 1) {
; #pragma unroll
;         for (int d = k >> 1; d > 0; d >>= 1) {
;           if (d >= 8) {
; #pragma unroll
;             for (int r = 0; r < 8; r++) {
;               const uint32_t o = (uint32_t)__shfl_xor((int)ks[r], d >> 3);
;               const bool up = (((j * 8 + r) & k) == 0), lower = (((j * 8) & d) == 0);
;               const uint32_t mn = ks[r] < o ? ks[r] : o, mx = ks[r] < o ? o : ks[r];
;               ks[r] = (lower == up) ? mn : mx;
;             }
;           } else {
; #pragma unroll
;             for (int r = 0; r < 8; r++) {
;               if ((r & d) == 0) {
;                 const bool up = (((j * 8 + r) & k) == 0);
;                 const uint32_t x0 = ks[r], x1 = ks[r | d];
;                 const uint32_t mn = x0 < x1 ? x0 : x1, mx = x0 < x1 ? x1 : x0;
;                 ks[r] = up ? mn : mx; ks[r | d] = up ? mx : mn;
;               }
;             }
;           }
;         }
;       }
	v_pk_mul_f32 v[84:85], v[92:93], v[102:103]
	v_pk_mul_f32 v[2:3], v[2:3], v[94:95]
	v_and_b32_sdwa v12, v11, v146 dst_sel:DWORD dst_unused:UNUSED_PAD src0_sel:WORD_1 src1_sel:DWORD
	v_and_b32_sdwa v86, v10, v146 dst_sel:DWORD dst_unused:UNUSED_PAD src0_sel:WORD_1 src1_sel:DWORD
	v_and_b32_sdwa v87, v5, v146 dst_sel:DWORD dst_unused:UNUSED_PAD src0_sel:WORD_1 src1_sel:DWORD
	v_and_b32_sdwa v88, v4, v146 dst_sel:DWORD dst_unused:UNUSED_PAD src0_sel:WORD_1 src1_sel:DWORD
	v_and_b32_sdwa v89, v81, v146 dst_sel:DWORD dst_unused:UNUSED_PAD src0_sel:WORD_1 src1_sel:DWORD
	v_and_b32_sdwa v90, v80, v146 dst_sel:DWORD dst_unused:UNUSED_PAD src0_sel:WORD_1 src1_sel:DWORD
	v_and_b32_sdwa v91, v7, v146 dst_sel:DWORD dst_unused:UNUSED_PAD src0_sel:WORD_1 src1_sel:DWORD
	v_and_b32_sdwa v92, v6, v146 dst_sel:DWORD dst_unused:UNUSED_PAD src0_sel:WORD_1 src1_sel:DWORD
	v_and_b32_sdwa v93, v83, v146 dst_sel:DWORD dst_unused:UNUSED_PAD src0_sel:WORD_1 src1_sel:DWORD
	v_and_b32_sdwa v94, v82, v146 dst_sel:DWORD dst_unused:UNUSED_PAD src0_sel:WORD_1 src1_sel:DWORD
	v_and_b32_sdwa v95, v9, v146 dst_sel:DWORD dst_unused:UNUSED_PAD src0_sel:WORD_1 src1_sel:DWORD
	v_and_b32_sdwa v96, v8, v146 dst_sel:DWORD dst_unused:UNUSED_PAD src0_sel:WORD_1 src1_sel:DWORD
	v_and_b32_sdwa v97, v85, v146 dst_sel:DWORD dst_unused:UNUSED_PAD src0_sel:WORD_1 src1_sel:DWORD
	v_and_b32_sdwa v98, v84, v146 dst_sel:DWORD dst_unused:UNUSED_PAD src0_sel:WORD_1 src1_sel:DWORD
	v_and_b32_sdwa v99, v3, v146 dst_sel:DWORD dst_unused:UNUSED_PAD src0_sel:WORD_1 src1_sel:DWORD
	v_and_b32_sdwa v100, v2, v146 dst_sel:DWORD dst_unused:UNUSED_PAD src0_sel:WORD_1 src1_sel:DWORD
	v_add3_u32 v11, v11, v12, s30
	v_add3_u32 v10, v10, v86, s30
	v_add3_u32 v5, v5, v87, s30
	v_add3_u32 v4, v4, v88, s30
	v_add3_u32 v12, v81, v89, s30
	v_add3_u32 v86, v80, v90, s30
	v_add3_u32 v7, v7, v91, s30
	v_add3_u32 v6, v6, v92, s30
	v_add3_u32 v88, v83, v93, s30
	v_add3_u32 v90, v82, v94, s30
	v_add3_u32 v9, v9, v95, s30
	v_add3_u32 v8, v8, v96, s30
	v_add3_u32 v92, v85, v97, s30
	v_add3_u32 v94, v84, v98, s30
	v_add3_u32 v3, v3, v99, s30
	v_add3_u32 v2, v2, v100, s30
	v_and_b32_e32 v81, 0xffff0000, v11
	v_and_b32_e32 v80, 0xffff0000, v10
	v_and_b32_e32 v83, 0xffff0000, v5
	v_and_b32_e32 v82, 0xffff0000, v4
	v_and_b32_e32 v85, 0xffff0000, v12
	v_and_b32_e32 v84, 0xffff0000, v86
	v_and_b32_e32 v87, 0xffff0000, v7
	v_and_b32_e32 v86, 0xffff0000, v6
	v_and_b32_e32 v89, 0xffff0000, v88
	v_and_b32_e32 v88, 0xffff0000, v90
	v_and_b32_e32 v91, 0xffff0000, v9
	v_and_b32_e32 v90, 0xffff0000, v8
	v_and_b32_e32 v93, 0xffff0000, v92
	v_and_b32_e32 v92, 0xffff0000, v94
	v_and_b32_e32 v95, 0xffff0000, v3
	v_and_b32_e32 v94, 0xffff0000, v2
	v_lshlrev_b64 v[0:1], 9, v[0:1]
	v_lshl_add_u64 v[10:11], v[16:17], 0, v[0:1]
	global_load_dwordx4 v[2:5], v[10:11], off
	global_load_dwordx4 v[6:9], v[10:11], off offset:16
	v_lshl_add_u64 v[0:1], s[22:23], 0, v[0:1]
	s_mov_b32 s26, -8
	s_waitcnt vmcnt(1)
	v_lshl_or_b32 v2, v2, 8, v132
	v_lshl_or_b32 v3, v3, 8, v135
	v_lshl_or_b32 v4, v4, 8, v136
	v_lshl_or_b32 v5, v5, 8, v137
	s_waitcnt vmcnt(0)
	v_lshl_or_b32 v6, v6, 8, v138
	v_lshl_or_b32 v7, v7, 8, v139
	v_lshl_or_b32 v8, v8, 8, v140
	v_lshl_or_b32 v9, v9, 8, v141
	v_min_u32_e32 v10, v2, v3
	v_max_u32_e32 v2, v2, v3
	v_min_u32_e32 v3, v4, v5
	v_max_u32_e32 v4, v4, v5
	v_min_u32_e32 v5, v6, v7
	v_max_u32_e32 v6, v6, v7
	v_min_u32_e32 v7, v8, v9
	v_max_u32_e32 v8, v8, v9
	v_min_u32_e32 v9, v10, v4
	v_max_u32_e32 v4, v10, v4
	v_min_u32_e32 v10, v2, v3
	v_max_u32_e32 v2, v2, v3
	v_min_u32_e32 v3, v5, v8
	v_max_u32_e32 v5, v5, v8
	v_min_u32_e32 v8, v6, v7
	v_max_u32_e32 v6, v6, v7
	v_min_u32_e32 v7, v9, v10
	v_max_u32_e32 v9, v9, v10
	v_min_u32_e32 v10, v4, v2
	v_max_u32_e32 v2, v4, v2
	v_min_u32_e32 v4, v5, v6
	v_max_u32_e32 v5, v5, v6
	v_min_u32_e32 v6, v3, v8
	v_max_u32_e32 v3, v3, v8
	v_min_u32_e32 v8, v7, v5
	v_max_u32_e32 v5, v7, v5
	v_min_u32_e32 v7, v9, v4
	v_max_u32_e32 v4, v9, v4
	v_min_u32_e32 v9, v10, v3
	v_max_u32_e32 v3, v10, v3
	v_min_u32_e32 v10, v2, v6
	v_max_u32_e32 v2, v2, v6
	v_cndmask_b32_e64 v6, v5, v8, s[4:5]
	v_cndmask_b32_e64 v5, v8, v5, s[4:5]
	v_cndmask_b32_e64 v8, v4, v7, s[4:5]
	v_cndmask_b32_e64 v4, v7, v4, s[4:5]
	v_cndmask_b32_e64 v7, v3, v9, s[4:5]
	v_cndmask_b32_e64 v3, v9, v3, s[4:5]
	v_cndmask_b32_e64 v9, v2, v10, s[4:5]
	v_cndmask_b32_e64 v2, v10, v2, s[4:5]
	v_min_u32_e32 v10, v6, v7
	v_max_u32_e32 v6, v6, v7
	v_min_u32_e32 v7, v8, v9
	v_max_u32_e32 v8, v8, v9
	v_min_u32_e32 v9, v5, v3
	v_max_u32_e32 v3, v5, v3
	v_min_u32_e32 v5, v4, v2
	v_max_u32_e32 v2, v4, v2
	v_cndmask_b32_e64 v4, v6, v10, s[4:5]
	v_cndmask_b32_e64 v6, v10, v6, s[4:5]
	v_cndmask_b32_e64 v10, v8, v7, s[4:5]
	v_cndmask_b32_e64 v7, v7, v8, s[4:5]
	v_cndmask_b32_e64 v8, v3, v9, s[4:5]
	v_cndmask_b32_e64 v3, v9, v3, s[4:5]
	v_cndmask_b32_e64 v9, v2, v5, s[4:5]
	v_cndmask_b32_e64 v2, v5, v2, s[4:5]
	v_min_u32_e32 v5, v4, v10
	v_max_u32_e32 v4, v4, v10
	v_min_u32_e32 v10, v6, v7
	v_max_u32_e32 v6, v6, v7
	v_min_u32_e32 v7, v8, v9
	v_max_u32_e32 v8, v8, v9
	v_min_u32_e32 v9, v3, v2
	v_max_u32_e32 v2, v3, v2
	v_cndmask_b32_e64 v3, v4, v5, s[4:5]
	v_cndmask_b32_e64 v4, v5, v4, s[4:5]
	v_cndmask_b32_e64 v5, v6, v10, s[4:5]
	v_cndmask_b32_e64 v6, v10, v6, s[4:5]
	v_cndmask_b32_e64 v10, v8, v7, s[4:5]
	v_cndmask_b32_e64 v7, v7, v8, s[4:5]
	v_cndmask_b32_e64 v8, v2, v9, s[4:5]
	v_cndmask_b32_e64 v2, v9, v2, s[4:5]
	ds_bpermute_b32 v9, v128, v3
	ds_bpermute_b32 v11, v128, v4
	ds_bpermute_b32 v12, v128, v5
	ds_bpermute_b32 v96, v128, v6
	ds_bpermute_b32 v97, v128, v10
	s_waitcnt lgkmcnt(4)
	v_min_u32_e32 v98, v3, v9
	v_max_u32_e32 v3, v3, v9
	s_waitcnt lgkmcnt(3)
; __device__ void phase_gather(const P& p, int vb, int nvb, char* smem) {
;     ...
; #pragma unroll
;       for (int k = 2; k <= 128; k <<= 1) {
; #pragma unroll
;         for (int d = k >> 1; d > 0; d >>= 1) {
;           if (d >= 8) {
; #pragma unroll
;             for (int r = 0; r < 8; r++) {
;               const uint32_t o = (uint32_t)__shfl_xor((int)ks[r], d >> 3);
;               const bool up = (((j * 8 + r) & k) == 0), lower = (((j * 8) & d) == 0);
;               const uint32_t mn = ks[r] < o ? ks[r] : o, mx = ks[r] < o ? o : ks[r];
;               ks[r] = (lower == up) ? mn : mx;
;             }
;           } else {
; #pragma unroll
;             for (int r = 0; r < 8; r++) {
;               if ((r & d) == 0) {
;                 const bool up = (((j * 8 + r) & k) == 0);
;                 const uint32_t x0 = ks[r], x1 = ks[r | d];
;                 const uint32_t mn = x0 < x1 ? x0 : x1, mx = x0 < x1 ? x1 : x0;
;                 ks[r] = up ? mn : mx; ks[r | d] = up ? mx : mn;
;               }
;             }
;           }
;         }
;       }
	v_min_u32_e32 v9, v4, v11
	v_max_u32_e32 v4, v4, v11
	v_cndmask_b32_e64 v4, v4, v9, s[6:7]
	ds_bpermute_b32 v9, v128, v7
	s_waitcnt lgkmcnt(3)
	v_min_u32_e32 v11, v5, v12
	v_max_u32_e32 v5, v5, v12
	s_waitcnt lgkmcnt(2)
	v_min_u32_e32 v12, v6, v96
	v_cndmask_b32_e64 v5, v5, v11, s[6:7]
	v_max_u32_e32 v6, v6, v96
	s_waitcnt lgkmcnt(1)
	v_min_u32_e32 v11, v10, v97
	v_max_u32_e32 v10, v10, v97
	v_cndmask_b32_e64 v6, v6, v12, s[6:7]
	v_cndmask_b32_e64 v10, v10, v11, s[6:7]
	ds_bpermute_b32 v11, v128, v8
	s_waitcnt lgkmcnt(1)
	v_min_u32_e32 v12, v7, v9
	v_max_u32_e32 v7, v7, v9
	ds_bpermute_b32 v9, v128, v2
	v_cndmask_b32_e64 v3, v3, v98, s[6:7]
	v_cndmask_b32_e64 v7, v7, v12, s[6:7]
	s_waitcnt lgkmcnt(1)
	v_min_u32_e32 v12, v8, v11
	v_max_u32_e32 v8, v8, v11
	s_waitcnt lgkmcnt(0)
	v_min_u32_e32 v11, v2, v9
	v_max_u32_e32 v2, v2, v9
	v_min_u32_e32 v9, v3, v10
	v_max_u32_e32 v3, v3, v10
	v_cndmask_b32_e64 v8, v8, v12, s[6:7]
	v_cndmask_b32_e64 v10, v3, v9, s[2:3]
	v_cndmask_b32_e64 v3, v9, v3, s[2:3]
	v_min_u32_e32 v9, v4, v7
	v_max_u32_e32 v4, v4, v7
	v_cndmask_b32_e64 v2, v2, v11, s[6:7]
	v_cndmask_b32_e64 v7, v4, v9, s[2:3]
	v_cndmask_b32_e64 v4, v9, v4, s[2:3]
	v_min_u32_e32 v9, v5, v8
	v_max_u32_e32 v5, v5, v8
	v_cndmask_b32_e64 v8, v5, v9, s[2:3]
	v_cndmask_b32_e64 v5, v9, v5, s[2:3]
	v_min_u32_e32 v9, v6, v2
	v_max_u32_e32 v2, v6, v2
	v_cndmask_b32_e64 v6, v2, v9, s[2:3]
	v_cndmask_b32_e64 v2, v9, v2, s[2:3]
	v_min_u32_e32 v9, v10, v8
	v_max_u32_e32 v8, v10, v8
	v_cndmask_b32_e64 v10, v8, v9, s[2:3]
	v_cndmask_b32_e64 v8, v9, v8, s[2:3]
	v_min_u32_e32 v9, v7, v6
	v_max_u32_e32 v6, v7, v6
	v_cndmask_b32_e64 v7, v6, v9, s[2:3]
	v_cndmask_b32_e64 v6, v9, v6, s[2:3]
	v_min_u32_e32 v9, v3, v5
	v_max_u32_e32 v3, v3, v5
	v_cndmask_b32_e64 v5, v3, v9, s[2:3]
	v_cndmask_b32_e64 v3, v9, v3, s[2:3]
	v_min_u32_e32 v9, v4, v2
	v_max_u32_e32 v2, v4, v2
	v_cndmask_b32_e64 v4, v2, v9, s[2:3]
	v_cndmask_b32_e64 v2, v9, v2, s[2:3]
	v_min_u32_e32 v9, v10, v7
	v_max_u32_e32 v7, v10, v7
	v_cndmask_b32_e64 v10, v7, v9, s[2:3]
	v_cndmask_b32_e64 v7, v9, v7, s[2:3]
	v_min_u32_e32 v9, v8, v6
	v_max_u32_e32 v6, v8, v6
	v_cndmask_b32_e64 v8, v6, v9, s[2:3]
	v_cndmask_b32_e64 v6, v9, v6, s[2:3]
	v_min_u32_e32 v9, v5, v4
	v_max_u32_e32 v4, v5, v4
	v_cndmask_b32_e64 v5, v4, v9, s[2:3]
	v_cndmask_b32_e64 v4, v9, v4, s[2:3]
	v_min_u32_e32 v9, v3, v2
	ds_bpermute_b32 v11, v129, v10
	v_max_u32_e32 v2, v3, v2
	v_cndmask_b32_e64 v3, v2, v9, s[2:3]
	v_cndmask_b32_e64 v2, v9, v2, s[2:3]
	ds_bpermute_b32 v9, v129, v7
	s_waitcnt lgkmcnt(1)
	v_min_u32_e32 v12, v10, v11
	v_max_u32_e32 v10, v10, v11
	ds_bpermute_b32 v11, v129, v8
	v_cndmask_b32_e64 v10, v10, v12, s[8:9]
	s_waitcnt lgkmcnt(1)
	v_min_u32_e32 v12, v7, v9
	v_max_u32_e32 v7, v7, v9
	ds_bpermute_b32 v9, v129, v6
	v_cndmask_b32_e64 v7, v7, v12, s[8:9]
	s_waitcnt lgkmcnt(1)
	v_min_u32_e32 v12, v8, v11
	v_max_u32_e32 v8, v8, v11
	ds_bpermute_b32 v11, v129, v5
	v_cndmask_b32_e64 v8, v8, v12, s[8:9]
	s_waitcnt lgkmcnt(1)
	v_min_u32_e32 v12, v6, v9
	v_max_u32_e32 v6, v6, v9
	ds_bpermute_b32 v9, v129, v4
	v_cndmask_b32_e64 v6, v6, v12, s[8:9]
	s_waitcnt lgkmcnt(1)
	v_min_u32_e32 v12, v5, v11
	v_max_u32_e32 v5, v5, v11
	ds_bpermute_b32 v11, v129, v3
	v_cndmask_b32_e64 v5, v5, v12, s[8:9]
	s_waitcnt lgkmcnt(1)
	v_min_u32_e32 v12, v4, v9
	v_max_u32_e32 v4, v4, v9
	ds_bpermute_b32 v9, v129, v2
	v_cndmask_b32_e64 v4, v4, v12, s[8:9]
	s_waitcnt lgkmcnt(1)
	v_min_u32_e32 v12, v3, v11
	v_max_u32_e32 v3, v3, v11
	ds_bpermute_b32 v11, v128, v10
	v_cndmask_b32_e64 v3, v3, v12, s[8:9]
	s_waitcnt lgkmcnt(1)
	v_min_u32_e32 v12, v2, v9
	v_max_u32_e32 v2, v2, v9
	ds_bpermute_b32 v9, v128, v7
	v_cndmask_b32_e64 v2, v2, v12, s[8:9]
	s_waitcnt lgkmcnt(1)
	v_min_u32_e32 v12, v10, v11
	v_max_u32_e32 v10, v10, v11
	ds_bpermute_b32 v11, v128, v8
	v_cndmask_b32_e64 v10, v10, v12, s[10:11]
	s_waitcnt lgkmcnt(1)
	v_min_u32_e32 v12, v7, v9
	v_max_u32_e32 v7, v7, v9
	ds_bpermute_b32 v9, v128, v6
	v_cndmask_b32_e64 v7, v7, v12, s[10:11]
	s_waitcnt lgkmcnt(1)
	v_min_u32_e32 v12, v8, v11
	v_max_u32_e32 v8, v8, v11
	ds_bpermute_b32 v11, v128, v5
	v_cndmask_b32_e64 v8, v8, v12, s[10:11]
	s_waitcnt lgkmcnt(1)
	v_min_u32_e32 v12, v6, v9
	v_max_u32_e32 v6, v6, v9
	ds_bpermute_b32 v9, v128, v4
	v_cndmask_b32_e64 v6, v6, v12, s[10:11]
	s_waitcnt lgkmcnt(1)
	v_min_u32_e32 v12, v5, v11
	v_max_u32_e32 v5, v5, v11
	v_cndmask_b32_e64 v5, v5, v12, s[10:11]
	ds_bpermute_b32 v11, v128, v3
	s_waitcnt lgkmcnt(1)
	v_min_u32_e32 v12, v4, v9
	v_max_u32_e32 v4, v4, v9
	ds_bpermute_b32 v9, v128, v2
	v_cndmask_b32_e64 v4, v4, v12, s[10:11]
	s_waitcnt lgkmcnt(1)
	v_min_u32_e32 v12, v3, v11
	v_max_u32_e32 v3, v3, v11
	v_cndmask_b32_e64 v3, v3, v12, s[10:11]
	s_waitcnt lgkmcnt(0)
	v_min_u32_e32 v11, v2, v9
	v_max_u32_e32 v2, v2, v9
	v_min_u32_e32 v9, v10, v5
	v_max_u32_e32 v5, v10, v5
	v_cndmask_b32_e64 v10, v5, v9, s[0:1]
	v_cndmask_b32_e64 v5, v9, v5, s[0:1]
	v_min_u32_e32 v9, v7, v4
	v_max_u32_e32 v4, v7, v4
	v_cndmask_b32_e64 v2, v2, v11, s[10:11]
	v_cndmask_b32_e64 v7, v4, v9, s[0:1]
	v_cndmask_b32_e64 v4, v9, v4, s[0:1]
	v_min_u32_e32 v9, v8, v3
	v_max_u32_e32 v3, v8, v3
	v_cndmask_b32_e64 v8, v3, v9, s[0:1]
	v_cndmask_b32_e64 v3, v9, v3, s[0:1]
	v_min_u32_e32 v9, v6, v2
	v_max_u32_e32 v2, v6, v2
	v_cndmask_b32_e64 v6, v2, v9, s[0:1]
	v_cndmask_b32_e64 v2, v9, v2, s[0:1]
	v_min_u32_e32 v9, v10, v8
	v_max_u32_e32 v8, v10, v8
	v_cndmask_b32_e64 v10, v8, v9, s[0:1]
	v_cndmask_b32_e64 v8, v9, v8, s[0:1]
	v_min_u32_e32 v9, v7, v6
	v_max_u32_e32 v6, v7, v6
	v_cndmask_b32_e64 v7, v6, v9, s[0:1]
	v_cndmask_b32_e64 v6, v9, v6, s[0:1]
	v_min_u32_e32 v9, v5, v3
	v_max_u32_e32 v3, v5, v3
	v_cndmask_b32_e64 v5, v3, v9, s[0:1]
	v_cndmask_b32_e64 v3, v9, v3, s[0:1]
	v_min_u32_e32 v9, v4, v2
	v_max_u32_e32 v2, v4, v2
	v_cndmask_b32_e64 v4, v2, v9, s[0:1]
	v_cndmask_b32_e64 v2, v9, v2, s[0:1]
	v_min_u32_e32 v9, v10, v7
	v_max_u32_e32 v7, v10, v7
	v_cndmask_b32_e64 v10, v7, v9, s[0:1]
	v_cndmask_b32_e64 v7, v9, v7, s[0:1]
	v_min_u32_e32 v9, v8, v6
	v_max_u32_e32 v6, v8, v6
	v_cndmask_b32_e64 v8, v6, v9, s[0:1]
	v_cndmask_b32_e64 v6, v9, v6, s[0:1]
	v_min_u32_e32 v9, v5, v4
	v_max_u32_e32 v4, v5, v4
	v_cndmask_b32_e64 v5, v4, v9, s[0:1]
	v_cndmask_b32_e64 v4, v9, v4, s[0:1]
	v_min_u32_e32 v9, v3, v2
	ds_bpermute_b32 v11, v130, v10
	v_max_u32_e32 v2, v3, v2
	v_cndmask_b32_e64 v3, v2, v9, s[0:1]
	v_cndmask_b32_e64 v2, v9, v2, s[0:1]
	ds_bpermute_b32 v9, v130, v7
	s_waitcnt lgkmcnt(1)
; __device__ void phase_gather(const P& p, int vb, int nvb, char* smem) {
;     ...
; #pragma unroll
;       for (int k = 2; k <= 128; k <<= 1) {
; #pragma unroll
;         for (int d = k >> 1; d > 0; d >>= 1) {
;           if (d >= 8) {
; #pragma unroll
;             for (int r = 0; r < 8; r++) {
;               const uint32_t o = (uint32_t)__shfl_xor((int)ks[r], d >> 3);
;               const bool up = (((j * 8 + r) & k) == 0), lower = (((j * 8) & d) == 0);
;               const uint32_t mn = ks[r] < o ? ks[r] : o, mx = ks[r] < o ? o : ks[r];
;               ks[r] = (lower == up) ? mn : mx;
;             }
;           } else {
; #pragma unroll
;             for (int r = 0; r < 8; r++) {
;               if ((r & d) == 0) {
;                 const bool up = (((j * 8 + r) & k) == 0);
;                 const uint32_t x0 = ks[r], x1 = ks[r | d];
;                 const uint32_t mn = x0 < x1 ? x0 : x1, mx = x0 < x1 ? x1 : x0;
;                 ks[r] = up ? mn : mx; ks[r | d] = up ? mx : mn;
;               }
;             }
;           }
;         }
;       }
	v_min_u32_e32 v12, v10, v11
	v_max_u32_e32 v10, v10, v11
	ds_bpermute_b32 v11, v130, v8
	v_cndmask_b32_e64 v10, v10, v12, s[12:13]
	s_waitcnt lgkmcnt(1)
	v_min_u32_e32 v12, v7, v9
	v_max_u32_e32 v7, v7, v9
	ds_bpermute_b32 v9, v130, v6
	v_cndmask_b32_e64 v7, v7, v12, s[12:13]
	s_waitcnt lgkmcnt(1)
	v_min_u32_e32 v12, v8, v11
	v_max_u32_e32 v8, v8, v11
	ds_bpermute_b32 v11, v130, v5
	v_cndmask_b32_e64 v8, v8, v12, s[12:13]
	s_waitcnt lgkmcnt(1)
	v_min_u32_e32 v12, v6, v9
	v_max_u32_e32 v6, v6, v9
	ds_bpermute_b32 v9, v130, v4
	v_cndmask_b32_e64 v6, v6, v12, s[12:13]
	s_waitcnt lgkmcnt(1)
	v_min_u32_e32 v12, v5, v11
	v_max_u32_e32 v5, v5, v11
	ds_bpermute_b32 v11, v130, v3
	v_cndmask_b32_e64 v5, v5, v12, s[12:13]
	s_waitcnt lgkmcnt(1)
	v_min_u32_e32 v12, v4, v9
	v_max_u32_e32 v4, v4, v9
	ds_bpermute_b32 v9, v130, v2
	v_cndmask_b32_e64 v4, v4, v12, s[12:13]
	s_waitcnt lgkmcnt(1)
	v_min_u32_e32 v12, v3, v11
	v_max_u32_e32 v3, v3, v11
	ds_bpermute_b32 v11, v129, v10
	v_cndmask_b32_e64 v3, v3, v12, s[12:13]
	s_waitcnt lgkmcnt(1)
	v_min_u32_e32 v12, v2, v9
	v_max_u32_e32 v2, v2, v9
	ds_bpermute_b32 v9, v129, v7
	v_cndmask_b32_e64 v2, v2, v12, s[12:13]
	s_waitcnt lgkmcnt(1)
	v_min_u32_e32 v12, v10, v11
	v_max_u32_e32 v10, v10, v11
	ds_bpermute_b32 v11, v129, v8
	v_cndmask_b32_e64 v10, v10, v12, s[14:15]
	s_waitcnt lgkmcnt(1)
	v_min_u32_e32 v12, v7, v9
	v_max_u32_e32 v7, v7, v9
	ds_bpermute_b32 v9, v129, v6
	v_cndmask_b32_e64 v7, v7, v12, s[14:15]
	s_waitcnt lgkmcnt(1)
	v_min_u32_e32 v12, v8, v11
	v_max_u32_e32 v8, v8, v11
	ds_bpermute_b32 v11, v129, v5
	v_cndmask_b32_e64 v8, v8, v12, s[14:15]
	s_waitcnt lgkmcnt(1)
	v_min_u32_e32 v12, v6, v9
	v_max_u32_e32 v6, v6, v9
	ds_bpermute_b32 v9, v129, v4
	v_cndmask_b32_e64 v6, v6, v12, s[14:15]
	s_waitcnt lgkmcnt(1)
	v_min_u32_e32 v12, v5, v11
	v_max_u32_e32 v5, v5, v11
	ds_bpermute_b32 v11, v129, v3
	v_cndmask_b32_e64 v5, v5, v12, s[14:15]
	s_waitcnt lgkmcnt(1)
	v_min_u32_e32 v12, v4, v9
	v_max_u32_e32 v4, v4, v9
	ds_bpermute_b32 v9, v129, v2
	v_cndmask_b32_e64 v4, v4, v12, s[14:15]
	s_waitcnt lgkmcnt(1)
	v_min_u32_e32 v12, v3, v11
	v_max_u32_e32 v3, v3, v11
	ds_bpermute_b32 v11, v128, v10
	v_cndmask_b32_e64 v3, v3, v12, s[14:15]
	s_waitcnt lgkmcnt(1)
	v_min_u32_e32 v12, v2, v9
	v_max_u32_e32 v2, v2, v9
	ds_bpermute_b32 v9, v128, v7
	v_cndmask_b32_e64 v2, v2, v12, s[14:15]
	s_waitcnt lgkmcnt(1)
	v_min_u32_e32 v12, v10, v11
	v_max_u32_e32 v10, v10, v11
	ds_bpermute_b32 v11, v128, v8
	v_cndmask_b32_e64 v10, v10, v12, s[16:17]
	s_waitcnt lgkmcnt(1)
	v_min_u32_e32 v12, v7, v9
	v_max_u32_e32 v7, v7, v9
	ds_bpermute_b32 v9, v128, v6
	v_cndmask_b32_e64 v7, v7, v12, s[16:17]
	s_waitcnt lgkmcnt(1)
	v_min_u32_e32 v12, v8, v11
	v_max_u32_e32 v8, v8, v11
	ds_bpermute_b32 v11, v128, v5
	v_cndmask_b32_e64 v8, v8, v12, s[16:17]
	s_waitcnt lgkmcnt(1)
	v_min_u32_e32 v12, v6, v9
	v_max_u32_e32 v6, v6, v9
	ds_bpermute_b32 v9, v128, v4
	v_cndmask_b32_e64 v6, v6, v12, s[16:17]
	s_waitcnt lgkmcnt(1)
	v_min_u32_e32 v12, v5, v11
	v_max_u32_e32 v5, v5, v11
	v_cndmask_b32_e64 v5, v5, v12, s[16:17]
	ds_bpermute_b32 v11, v128, v3
	s_waitcnt lgkmcnt(1)
	v_min_u32_e32 v12, v4, v9
	v_max_u32_e32 v4, v4, v9
	ds_bpermute_b32 v9, v128, v2
	v_cndmask_b32_e64 v4, v4, v12, s[16:17]
	s_waitcnt lgkmcnt(1)
	v_min_u32_e32 v12, v3, v11
	v_max_u32_e32 v3, v3, v11
	v_cndmask_b32_e64 v3, v3, v12, s[16:17]
	s_waitcnt lgkmcnt(0)
	v_min_u32_e32 v11, v2, v9
	v_max_u32_e32 v2, v2, v9
	v_min_u32_e32 v9, v10, v5
	v_max_u32_e32 v5, v10, v5
	v_cndmask_b32_e64 v10, v5, v9, s[18:19]
	v_cndmask_b32_e64 v5, v9, v5, s[18:19]
	v_min_u32_e32 v9, v7, v4
	v_max_u32_e32 v4, v7, v4
	v_cndmask_b32_e64 v2, v2, v11, s[16:17]
	v_cndmask_b32_e64 v7, v4, v9, s[18:19]
	v_cndmask_b32_e64 v4, v9, v4, s[18:19]
	v_min_u32_e32 v9, v8, v3
	v_max_u32_e32 v3, v8, v3
	v_cndmask_b32_e64 v8, v3, v9, s[18:19]
	v_cndmask_b32_e64 v3, v9, v3, s[18:19]
	v_min_u32_e32 v9, v6, v2
	v_max_u32_e32 v2, v6, v2
	v_cndmask_b32_e64 v6, v2, v9, s[18:19]
	v_cndmask_b32_e64 v2, v9, v2, s[18:19]
	v_min_u32_e32 v9, v10, v8
	v_max_u32_e32 v8, v10, v8
	v_cndmask_b32_e64 v10, v8, v9, s[18:19]
	v_cndmask_b32_e64 v8, v9, v8, s[18:19]
	v_min_u32_e32 v9, v7, v6
	v_max_u32_e32 v6, v7, v6
	v_cndmask_b32_e64 v7, v6, v9, s[18:19]
	v_cndmask_b32_e64 v6, v9, v6, s[18:19]
	v_min_u32_e32 v9, v5, v3
	v_max_u32_e32 v3, v5, v3
	v_cndmask_b32_e64 v5, v3, v9, s[18:19]
	v_cndmask_b32_e64 v3, v9, v3, s[18:19]
	v_min_u32_e32 v9, v4, v2
	v_max_u32_e32 v2, v4, v2
	v_cndmask_b32_e64 v4, v2, v9, s[18:19]
	v_cndmask_b32_e64 v2, v9, v2, s[18:19]
	v_min_u32_e32 v9, v10, v7
	v_max_u32_e32 v7, v10, v7
	v_cndmask_b32_e64 v10, v7, v9, s[18:19]
	v_cndmask_b32_e64 v7, v9, v7, s[18:19]
	v_min_u32_e32 v9, v8, v6
	v_max_u32_e32 v6, v8, v6
	v_cndmask_b32_e64 v8, v6, v9, s[18:19]
	v_cndmask_b32_e64 v6, v9, v6, s[18:19]
	v_min_u32_e32 v9, v5, v4
	v_max_u32_e32 v4, v5, v4
	v_cndmask_b32_e64 v5, v4, v9, s[18:19]
	v_cndmask_b32_e64 v4, v9, v4, s[18:19]
	v_min_u32_e32 v9, v3, v2
	ds_bpermute_b32 v11, v131, v10
	v_max_u32_e32 v2, v3, v2
	v_cndmask_b32_e64 v3, v2, v9, s[18:19]
	v_cndmask_b32_e64 v2, v9, v2, s[18:19]
	ds_bpermute_b32 v9, v131, v7
	s_waitcnt lgkmcnt(1)
	v_min_u32_e32 v12, v10, v11
	v_max_u32_e32 v10, v10, v11
	ds_bpermute_b32 v11, v131, v8
	v_cndmask_b32_e64 v10, v10, v12, s[18:19]
	s_waitcnt lgkmcnt(1)
	v_min_u32_e32 v12, v7, v9
	v_max_u32_e32 v7, v7, v9
	ds_bpermute_b32 v9, v131, v6
	v_cndmask_b32_e64 v7, v7, v12, s[18:19]
	s_waitcnt lgkmcnt(1)
	v_min_u32_e32 v12, v8, v11
	v_max_u32_e32 v8, v8, v11
	ds_bpermute_b32 v11, v131, v5
	v_cndmask_b32_e64 v8, v8, v12, s[18:19]
	s_waitcnt lgkmcnt(1)
; __device__ void phase_gather(const P& p, int vb, int nvb, char* smem) {
;     ...
;       for (int k = 2; k <= 128; k <<= 1) {
; #pragma unroll
;         for (int d = k >> 1; d > 0; d >>= 1) {
;           if (d >= 8) {
; #pragma unroll
;             for (int r = 0; r < 8; r++) {
;               const uint32_t o = (uint32_t)__shfl_xor((int)ks[r], d >> 3);
;               const bool up = (((j * 8 + r) & k) == 0), lower = (((j * 8) & d) == 0);
;               const uint32_t mn = ks[r] < o ? ks[r] : o, mx = ks[r] < o ? o : ks[r];
;               ks[r] = (lower == up) ? mn : mx;
;             }
;           } else {
; #pragma unroll
;             for (int r = 0; r < 8; r++) {
;               if ((r & d) == 0) {
;                 const bool up = (((j * 8 + r) & k) == 0);
;                 const uint32_t x0 = ks[r], x1 = ks[r | d];
;                 const uint32_t mn = x0 < x1 ? x0 : x1, mx = x0 < x1 ? x1 : x0;
;                 ks[r] = up ? mn : mx; ks[r | d] = up ? mx : mn;
;               }
;             }
;           }
;         }
;       }
;       *(uint4*)(kl + g * 128 + j * 8) = make_uint4(ks[0], ks[1], ks[2], ks[3]);
;       *(uint4*)(kl + g * 128 + j * 8 + 4) = make_uint4(ks[4], ks[5], ks[6], ks[7]);
;     }
;     asm volatile("s_waitcnt lgkmcnt(0)" ::: "memory");
;     const float* sgp = selg + (size_t)rr * 128;
;     const uint32_t* mykl = kl + g * 128;
;     float* mywl = wl + g * 128;
;     float gpre[8];
; #pragma unroll
;     for (int m = 0; m < 8; m++) gpre[m] = sgp[mykl[j + 16 * m] & 127u];
	v_min_u32_e32 v12, v6, v9
	v_max_u32_e32 v6, v6, v9
	ds_bpermute_b32 v9, v131, v4
	v_cndmask_b32_e64 v6, v6, v12, s[18:19]
	s_waitcnt lgkmcnt(1)
	v_min_u32_e32 v12, v5, v11
	v_max_u32_e32 v5, v5, v11
	ds_bpermute_b32 v11, v131, v3
	v_cndmask_b32_e64 v5, v5, v12, s[18:19]
	s_waitcnt lgkmcnt(1)
	v_min_u32_e32 v12, v4, v9
	v_max_u32_e32 v4, v4, v9
	ds_bpermute_b32 v9, v131, v2
	v_cndmask_b32_e64 v4, v4, v12, s[18:19]
	s_waitcnt lgkmcnt(1)
	v_min_u32_e32 v12, v3, v11
	v_max_u32_e32 v3, v3, v11
	ds_bpermute_b32 v11, v130, v10
	v_cndmask_b32_e64 v3, v3, v12, s[18:19]
	s_waitcnt lgkmcnt(1)
	v_min_u32_e32 v12, v2, v9
	v_max_u32_e32 v2, v2, v9
	ds_bpermute_b32 v9, v130, v7
	v_cndmask_b32_e64 v2, v2, v12, s[18:19]
	s_waitcnt lgkmcnt(1)
	v_min_u32_e32 v12, v10, v11
	v_max_u32_e32 v10, v10, v11
	ds_bpermute_b32 v11, v130, v8
	v_cndmask_b32_e64 v10, v10, v12, s[0:1]
	s_waitcnt lgkmcnt(1)
	v_min_u32_e32 v12, v7, v9
	v_max_u32_e32 v7, v7, v9
	ds_bpermute_b32 v9, v130, v6
	v_cndmask_b32_e64 v7, v7, v12, s[0:1]
	s_waitcnt lgkmcnt(1)
	v_min_u32_e32 v12, v8, v11
	v_max_u32_e32 v8, v8, v11
	ds_bpermute_b32 v11, v130, v5
	v_cndmask_b32_e64 v8, v8, v12, s[0:1]
	s_waitcnt lgkmcnt(1)
	v_min_u32_e32 v12, v6, v9
	v_max_u32_e32 v6, v6, v9
	ds_bpermute_b32 v9, v130, v4
	v_cndmask_b32_e64 v6, v6, v12, s[0:1]
	s_waitcnt lgkmcnt(1)
	v_min_u32_e32 v12, v5, v11
	v_max_u32_e32 v5, v5, v11
	ds_bpermute_b32 v11, v130, v3
	v_cndmask_b32_e64 v5, v5, v12, s[0:1]
	s_waitcnt lgkmcnt(1)
	v_min_u32_e32 v12, v4, v9
	v_max_u32_e32 v4, v4, v9
	ds_bpermute_b32 v9, v130, v2
	v_cndmask_b32_e64 v4, v4, v12, s[0:1]
	s_waitcnt lgkmcnt(1)
	v_min_u32_e32 v12, v3, v11
	v_max_u32_e32 v3, v3, v11
	ds_bpermute_b32 v11, v129, v10
	v_cndmask_b32_e64 v3, v3, v12, s[0:1]
	s_waitcnt lgkmcnt(1)
	v_min_u32_e32 v12, v2, v9
	v_max_u32_e32 v2, v2, v9
	ds_bpermute_b32 v9, v129, v7
	v_cndmask_b32_e64 v2, v2, v12, s[0:1]
	s_waitcnt lgkmcnt(1)
	v_min_u32_e32 v12, v10, v11
	v_max_u32_e32 v10, v10, v11
	ds_bpermute_b32 v11, v129, v8
	v_cndmask_b32_e64 v10, v10, v12, s[2:3]
	s_waitcnt lgkmcnt(1)
	v_min_u32_e32 v12, v7, v9
	v_max_u32_e32 v7, v7, v9
	ds_bpermute_b32 v9, v129, v6
	v_cndmask_b32_e64 v7, v7, v12, s[2:3]
	s_waitcnt lgkmcnt(1)
	v_min_u32_e32 v12, v8, v11
	v_max_u32_e32 v8, v8, v11
	ds_bpermute_b32 v11, v129, v5
	v_cndmask_b32_e64 v8, v8, v12, s[2:3]
	s_waitcnt lgkmcnt(1)
	v_min_u32_e32 v12, v6, v9
	v_max_u32_e32 v6, v6, v9
	ds_bpermute_b32 v9, v129, v4
	v_cndmask_b32_e64 v6, v6, v12, s[2:3]
	s_waitcnt lgkmcnt(1)
	v_min_u32_e32 v12, v5, v11
	v_max_u32_e32 v5, v5, v11
	ds_bpermute_b32 v11, v129, v3
	v_cndmask_b32_e64 v5, v5, v12, s[2:3]
	s_waitcnt lgkmcnt(1)
	v_min_u32_e32 v12, v4, v9
	v_max_u32_e32 v4, v4, v9
	ds_bpermute_b32 v9, v129, v2
	v_cndmask_b32_e64 v4, v4, v12, s[2:3]
	s_waitcnt lgkmcnt(1)
	v_min_u32_e32 v12, v3, v11
	v_max_u32_e32 v3, v3, v11
	ds_bpermute_b32 v11, v128, v10
	v_cndmask_b32_e64 v3, v3, v12, s[2:3]
	s_waitcnt lgkmcnt(1)
	v_min_u32_e32 v12, v2, v9
	v_max_u32_e32 v2, v2, v9
	ds_bpermute_b32 v9, v128, v7
	v_cndmask_b32_e64 v2, v2, v12, s[2:3]
	s_waitcnt lgkmcnt(1)
	v_min_u32_e32 v12, v10, v11
	v_max_u32_e32 v10, v10, v11
	ds_bpermute_b32 v11, v128, v8
	v_cndmask_b32_e64 v10, v10, v12, s[4:5]
	s_waitcnt lgkmcnt(1)
	v_min_u32_e32 v12, v7, v9
	v_max_u32_e32 v7, v7, v9
	ds_bpermute_b32 v9, v128, v6
	v_cndmask_b32_e64 v7, v7, v12, s[4:5]
	s_waitcnt lgkmcnt(1)
	v_min_u32_e32 v12, v8, v11
	v_max_u32_e32 v8, v8, v11
	ds_bpermute_b32 v11, v128, v5
	v_cndmask_b32_e64 v8, v8, v12, s[4:5]
	s_waitcnt lgkmcnt(1)
	v_min_u32_e32 v12, v6, v9
	v_max_u32_e32 v6, v6, v9
	ds_bpermute_b32 v9, v128, v4
	v_cndmask_b32_e64 v6, v6, v12, s[4:5]
	s_waitcnt lgkmcnt(1)
	v_min_u32_e32 v12, v5, v11
	v_max_u32_e32 v5, v5, v11
	v_cndmask_b32_e64 v5, v5, v12, s[4:5]
	ds_bpermute_b32 v11, v128, v3
	s_waitcnt lgkmcnt(1)
	v_min_u32_e32 v12, v4, v9
	v_max_u32_e32 v4, v4, v9
	ds_bpermute_b32 v9, v128, v2
	v_cndmask_b32_e64 v4, v4, v12, s[4:5]
	s_waitcnt lgkmcnt(1)
	v_min_u32_e32 v12, v3, v11
	v_max_u32_e32 v3, v3, v11
	v_cndmask_b32_e64 v3, v3, v12, s[4:5]
	s_waitcnt lgkmcnt(0)
	v_min_u32_e32 v11, v2, v9
	v_max_u32_e32 v2, v2, v9
	v_cndmask_b32_e64 v2, v2, v11, s[4:5]
	v_min_u32_e32 v9, v10, v5
	v_max_u32_e32 v5, v10, v5
	v_min_u32_e32 v10, v7, v4
	v_max_u32_e32 v4, v7, v4
	v_min_u32_e32 v7, v8, v3
	v_max_u32_e32 v3, v8, v3
	v_min_u32_e32 v8, v6, v2
	v_max_u32_e32 v2, v6, v2
	v_min_u32_e32 v6, v9, v7
	v_max_u32_e32 v7, v9, v7
	v_min_u32_e32 v9, v10, v8
	v_max_u32_e32 v8, v10, v8
	v_min_u32_e32 v10, v5, v3
	v_max_u32_e32 v11, v5, v3
	v_min_u32_e32 v12, v4, v2
	v_max_u32_e32 v96, v4, v2
	v_min_u32_e32 v2, v6, v9
	v_max_u32_e32 v3, v6, v9
	v_min_u32_e32 v4, v7, v8
	v_max_u32_e32 v5, v7, v8
	v_min_u32_e32 v6, v10, v12
	v_max_u32_e32 v7, v10, v12
	v_min_u32_e32 v8, v11, v96
	v_max_u32_e32 v9, v11, v96
	ds_write_b128 v134, v[2:5]
	ds_write_b128 v134, v[6:9] offset:16
	s_waitcnt lgkmcnt(0)
	ds_read2_b32 v[2:3], v144 offset1:16
	ds_read2_b32 v[4:5], v144 offset0:32 offset1:48
	ds_read2_b32 v[8:9], v144 offset0:64 offset1:80
	ds_read2_b32 v[96:97], v144 offset0:96 offset1:112
	s_waitcnt lgkmcnt(3)
	v_and_b32_e32 v2, 0x7f, v2
	v_lshlrev_b32_e32 v12, 2, v2
	v_and_b32_e32 v2, 0x7f, v3
	v_lshl_add_u64 v[6:7], v[0:1], 0, v[12:13]
	v_lshlrev_b32_e32 v12, 2, v2
	s_waitcnt lgkmcnt(2)
	v_and_b32_e32 v4, 0x7f, v4
	v_lshl_add_u64 v[2:3], v[0:1], 0, v[12:13]
	v_lshlrev_b32_e32 v12, 2, v4
	v_and_b32_e32 v4, 0x7f, v5
	v_lshl_add_u64 v[10:11], v[0:1], 0, v[12:13]
	v_lshlrev_b32_e32 v12, 2, v4
	s_waitcnt lgkmcnt(1)
	v_and_b32_e32 v8, 0x7f, v8
	v_lshl_add_u64 v[4:5], v[0:1], 0, v[12:13]
	v_lshlrev_b32_e32 v12, 2, v8
	v_and_b32_e32 v8, 0x7f, v9
	v_lshl_add_u64 v[104:105], v[0:1], 0, v[12:13]
	v_lshlrev_b32_e32 v12, 2, v8
	v_lshl_add_u64 v[8:9], v[0:1], 0, v[12:13]
	s_waitcnt lgkmcnt(0)
	v_and_b32_e32 v12, 0x7f, v96
	v_lshlrev_b32_e32 v12, 2, v12
	v_lshl_add_u64 v[106:107], v[0:1], 0, v[12:13]
	v_and_b32_e32 v12, 0x7f, v97
	v_lshlrev_b32_e32 v12, 2, v12
	v_lshl_add_u64 v[0:1], v[0:1], 0, v[12:13]
	global_load_dword v103, v[6:7], off
	global_load_dword v102, v[2:3], off
	global_load_dword v101, v[10:11], off
	global_load_dword v100, v[4:5], off
	global_load_dword v99, v[104:105], off
	global_load_dword v98, v[8:9], off
	global_load_dword v97, v[106:107], off
	global_load_dword v96, v[0:1], off
	v_lshlrev_b32_e32 v250, 1, v132
	v_mov_b32_e32 v104, 0
	v_mov_b32_e32 v105, 0
	v_mov_b32_e32 v106, 0
	v_mov_b32_e32 v107, 0
	ds_read_b128 v[0:3], v133
	ds_read_b128 v[4:7], v133 offset:16
	ds_write_b128 v134, v[104:107] offset:2048
	ds_write_b128 v134, v[104:107] offset:2064
	s_lshl_b32 s27, s83, 22
	v_add_u32_e32 v230, s27, v250
	v_add_u32_e32 v231, v133, v142
	v_add_u32_e32 v251, v133, v142
	v_add_u32_e32 v254, 64, v133
	s_mov_b32 s26, 0
	s_mov_b32 s27, s83
	s_cmp_eq_u32 s27, 0
	s_cbranch_scc1 .Lgu_p_0
; __device__ void phase_gather(const P& p, int vb, int nvb, char* smem) {
;     ...
;         f32x2 d2 = f32x2{0.f, 0.f};
; #pragma unroll
;         for (int i = 0; i < 4; i++) {
;           const uint32_t w[4] = {uu[i].x, uu[i].y, uu[i].z, uu[i].w};
; #pragma unroll
;           for (int q = 0; q < 4; q++) {
;             d2 += __builtin_amdgcn_cvt_pk_f32_fp8((int)w[q], false) * xf[i * 8 + q * 2 + 0];
;             d2 += __builtin_amdgcn_cvt_pk_f32_fp8((int)w[q], true) * xf[i * 8 + q * 2 + 1];
;           }
	s_cmp_eq_u32 s27, 1
	s_cbranch_scc1 .Lgu_p_1
	s_cmp_eq_u32 s27, 2
	s_cbranch_scc1 .Lgu_p_2
	v_cvt_pk_bf16_f32 v214, v80, v81
	v_cvt_pk_bf16_f32 v215, v82, v83
	v_cvt_pk_bf16_f32 v216, v84, v85
	v_cvt_pk_bf16_f32 v217, v86, v87
	v_cvt_pk_bf16_f32 v218, v88, v89
	v_cvt_pk_bf16_f32 v219, v90, v91
	v_cvt_pk_bf16_f32 v220, v92, v93
	v_cvt_pk_bf16_f32 v221, v94, v95
	s_branch .Lgu_p_x
.Lgu_p_0:
	v_cvt_pk_bf16_f32 v214, v32, v33
	v_cvt_pk_bf16_f32 v215, v34, v35
	v_cvt_pk_bf16_f32 v216, v36, v37
	v_cvt_pk_bf16_f32 v217, v38, v39
	v_cvt_pk_bf16_f32 v218, v40, v41
	v_cvt_pk_bf16_f32 v219, v42, v43
	v_cvt_pk_bf16_f32 v220, v44, v45
	v_cvt_pk_bf16_f32 v221, v46, v47
	s_branch .Lgu_p_x
.Lgu_p_1:
	v_cvt_pk_bf16_f32 v214, v48, v49
	v_cvt_pk_bf16_f32 v215, v50, v51
	v_cvt_pk_bf16_f32 v216, v52, v53
	v_cvt_pk_bf16_f32 v217, v54, v55
	v_cvt_pk_bf16_f32 v218, v56, v57
	v_cvt_pk_bf16_f32 v219, v58, v59
	v_cvt_pk_bf16_f32 v220, v60, v61
	v_cvt_pk_bf16_f32 v221, v62, v63
	s_branch .Lgu_p_x
.Lgu_p_2:
	v_cvt_pk_bf16_f32 v214, v64, v65
	v_cvt_pk_bf16_f32 v215, v66, v67
	v_cvt_pk_bf16_f32 v216, v68, v69
	v_cvt_pk_bf16_f32 v217, v70, v71
	v_cvt_pk_bf16_f32 v218, v72, v73
	v_cvt_pk_bf16_f32 v219, v74, v75
	v_cvt_pk_bf16_f32 v220, v76, v77
	v_cvt_pk_bf16_f32 v221, v78, v79

; __device__ void phase_gather(const P& p, int vb, int nvb, char* smem) {
;     ...
;     for (int b0 = 0; b0 < 128; b0 += 8) {
;       float dp[8];
; #pragma unroll
;       for (int u = 0; u < 8; u++) {
;         const uint32_t key = mykl[b0 + u];
;         const int e = (int)(key >> 7);
;         const uint4* up = (const uint4*)(U + (size_t)e * 1024 + 16 * j);
;         uint4 uu[4];
; #pragma unroll
;         for (int i = 0; i < 4; i++) uu[i] = up[i * 16];
;         f32x2 d2 = f32x2{0.f, 0.f};
; #pragma unroll
;         for (int i = 0; i < 4; i++) {
;           const uint32_t w[4] = {uu[i].x, uu[i].y, uu[i].z, uu[i].w};
; #pragma unroll
;           for (int q = 0; q < 4; q++) {
;             d2 += __builtin_amdgcn_cvt_pk_f32_fp8((int)w[q], false) * xf[i * 8 + q * 2 + 0];
;             d2 += __builtin_amdgcn_cvt_pk_f32_fp8((int)w[q], true) * xf[i * 8 + q * 2 + 1];
;           }
.Lgu_iter:
	s_and_b32 s27, s26, 7
	s_cmp_lg_u32 s27, 0
	s_cbranch_scc1 .Lgu_body
	s_lshr_b32 s27, s26, 3
	s_and_b32 s27, s27, 3
	s_cmp_eq_u32 s27, 0
	s_cbranch_scc1 .Lgu_s_0
	s_cmp_eq_u32 s27, 1
	s_cbranch_scc1 .Lgu_s_1
	s_cmp_eq_u32 s27, 2
	s_cbranch_scc1 .Lgu_s_2
	v_cvt_pk_bf16_f32 v214, v80, v81
	v_cvt_pk_bf16_f32 v215, v82, v83
	v_cvt_pk_bf16_f32 v216, v84, v85
	v_cvt_pk_bf16_f32 v217, v86, v87
	v_cvt_pk_bf16_f32 v218, v88, v89
	v_cvt_pk_bf16_f32 v219, v90, v91
	v_cvt_pk_bf16_f32 v220, v92, v93
	v_cvt_pk_bf16_f32 v221, v94, v95
	s_branch .Lgu_s_x

; __device__ void phase_gather(const P& p, int vb, int nvb, char* smem) {
;     ...
;     for (int b0 = 0; b0 < 128; b0 += 8) {
;       float dp[8];
; #pragma unroll
;       for (int u = 0; u < 8; u++) {
;         const uint32_t key = mykl[b0 + u];
;         const int e = (int)(key >> 7);
;         const uint4* up = (const uint4*)(U + (size_t)e * 1024 + 16 * j);
;         uint4 uu[4];
; #pragma unroll
;         for (int i = 0; i < 4; i++) uu[i] = up[i * 16];
;         f32x2 d2 = f32x2{0.f, 0.f};
; #pragma unroll
;         for (int i = 0; i < 4; i++) {
;           const uint32_t w[4] = {uu[i].x, uu[i].y, uu[i].z, uu[i].w};
; #pragma unroll
;           for (int q = 0; q < 4; q++) {
;             d2 += __builtin_amdgcn_cvt_pk_f32_fp8((int)w[q], false) * xf[i * 8 + q * 2 + 0];
;             d2 += __builtin_amdgcn_cvt_pk_f32_fp8((int)w[q], true) * xf[i * 8 + q * 2 + 1];
;           }
;         }
;         dp[u] = d2.x + d2.y;
;       }
;       const bool h8 = (j & 8) != 0, h4 = (j & 4) != 0, h2b = (j & 2) != 0;
;       float q4[4], q2[2];
; #pragma unroll
;       for (int k = 0; k < 4; k++) { const float snd = h8 ? dp[k] : dp[k + 4], kp = h8 ? dp[k + 4] : dp[k]; q4[k] = kp + __shfl_xor(snd, 8); }
; #pragma unroll
;       for (int k = 0; k < 2; k++) { const float snd = h4 ? q4[k] : q4[k + 2], kp = h4 ? q4[k + 2] : q4[k]; q2[k] = kp + __shfl_xor(snd, 4); }
;       const float snd1 = h2b ? q2[0] : q2[1], kp1 = h2b ? q2[1] : q2[0];
;       float q1 = kp1 + __shfl_xor(snd1, 2);
;       q1 += __shfl_xor(q1, 1);
;       if ((j & 1) == 0) mywl[b0 + (j >> 1)] = q1;
.Lgu_s_x:
.Lgu_body:
	s_cmp_eq_u32 s26, 31
	s_cbranch_scc1 .Lgu_last
	s_waitcnt lgkmcnt(0)
	s_waitcnt vmcnt(15)
	v_cvt_scalef32_pk_bf16_fp8 v104, v150, 1.0
	v_cvt_scalef32_pk_bf16_fp8 v106, v150, 1.0 op_sel:[1,0,0]
	v_dot2_f32_bf16 v116, v104, v214, 0
	v_cvt_scalef32_pk_bf16_fp8 v108, v151, 1.0
	v_dot2c_f32_bf16_e32 v116, v106, v215
	v_cvt_scalef32_pk_bf16_fp8 v110, v151, 1.0 op_sel:[1,0,0]
	v_dot2c_f32_bf16_e32 v116, v108, v216
	v_cvt_scalef32_pk_bf16_fp8 v104, v152, 1.0
	v_dot2c_f32_bf16_e32 v116, v110, v217
	v_cvt_scalef32_pk_bf16_fp8 v106, v152, 1.0 op_sel:[1,0,0]
	v_dot2c_f32_bf16_e32 v116, v104, v218
	v_cvt_scalef32_pk_bf16_fp8 v108, v153, 1.0
	v_dot2c_f32_bf16_e32 v116, v106, v219
	v_cvt_scalef32_pk_bf16_fp8 v110, v153, 1.0 op_sel:[1,0,0]
	v_dot2c_f32_bf16_e32 v116, v108, v220
	v_and_or_b32 v8, v0, s66, v230
	v_dot2c_f32_bf16_e32 v116, v110, v221
	global_load_dwordx4 v[150:153], v8, s[98:99]
	s_waitcnt vmcnt(15)
	v_cvt_scalef32_pk_bf16_fp8 v104, v154, 1.0
	v_cvt_scalef32_pk_bf16_fp8 v106, v154, 1.0 op_sel:[1,0,0]
	v_dot2_f32_bf16 v117, v104, v214, 0
	v_cvt_scalef32_pk_bf16_fp8 v108, v155, 1.0
	v_dot2c_f32_bf16_e32 v117, v106, v215
	v_cvt_scalef32_pk_bf16_fp8 v110, v155, 1.0 op_sel:[1,0,0]
	v_dot2c_f32_bf16_e32 v117, v108, v216
	v_cvt_scalef32_pk_bf16_fp8 v104, v156, 1.0
	v_dot2c_f32_bf16_e32 v117, v110, v217
	v_cvt_scalef32_pk_bf16_fp8 v106, v156, 1.0 op_sel:[1,0,0]
	v_dot2c_f32_bf16_e32 v117, v104, v218
	v_cvt_scalef32_pk_bf16_fp8 v108, v157, 1.0
	v_dot2c_f32_bf16_e32 v117, v106, v219
	v_cvt_scalef32_pk_bf16_fp8 v110, v157, 1.0 op_sel:[1,0,0]
	v_dot2c_f32_bf16_e32 v117, v108, v220
	v_and_or_b32 v9, v1, s66, v230
	v_dot2c_f32_bf16_e32 v117, v110, v221
	global_load_dwordx4 v[154:157], v9, s[98:99]
	ds_read_b128 v[4:7], v254 offset:16
	s_waitcnt vmcnt(15)
	v_cvt_scalef32_pk_bf16_fp8 v104, v158, 1.0
	v_cvt_scalef32_pk_bf16_fp8 v106, v158, 1.0 op_sel:[1,0,0]
	v_dot2_f32_bf16 v118, v104, v214, 0
	v_cvt_scalef32_pk_bf16_fp8 v108, v159, 1.0
	v_dot2c_f32_bf16_e32 v118, v106, v215
	v_cvt_scalef32_pk_bf16_fp8 v110, v159, 1.0 op_sel:[1,0,0]
	v_dot2c_f32_bf16_e32 v118, v108, v216
	v_cvt_scalef32_pk_bf16_fp8 v104, v160, 1.0
	v_dot2c_f32_bf16_e32 v118, v110, v217
	v_cvt_scalef32_pk_bf16_fp8 v106, v160, 1.0 op_sel:[1,0,0]
	v_dot2c_f32_bf16_e32 v118, v104, v218
	v_cvt_scalef32_pk_bf16_fp8 v108, v161, 1.0
	v_dot2c_f32_bf16_e32 v118, v106, v219
	v_cvt_scalef32_pk_bf16_fp8 v110, v161, 1.0 op_sel:[1,0,0]
	v_dot2c_f32_bf16_e32 v118, v108, v220
	v_and_or_b32 v8, v2, s66, v230
	v_dot2c_f32_bf16_e32 v118, v110, v221
	global_load_dwordx4 v[158:161], v8, s[98:99]
	s_waitcnt vmcnt(15)
	v_cvt_scalef32_pk_bf16_fp8 v104, v162, 1.0
	v_cvt_scalef32_pk_bf16_fp8 v106, v162, 1.0 op_sel:[1,0,0]
	v_dot2_f32_bf16 v119, v104, v214, 0
	v_cvt_scalef32_pk_bf16_fp8 v108, v163, 1.0
	v_dot2c_f32_bf16_e32 v119, v106, v215
	v_cvt_scalef32_pk_bf16_fp8 v110, v163, 1.0 op_sel:[1,0,0]
	v_dot2c_f32_bf16_e32 v119, v108, v216
	v_cvt_scalef32_pk_bf16_fp8 v104, v164, 1.0
	v_dot2c_f32_bf16_e32 v119, v110, v217
	v_cvt_scalef32_pk_bf16_fp8 v106, v164, 1.0 op_sel:[1,0,0]
	v_dot2c_f32_bf16_e32 v119, v104, v218
	v_cvt_scalef32_pk_bf16_fp8 v108, v165, 1.0
	v_dot2c_f32_bf16_e32 v119, v106, v219
	v_cvt_scalef32_pk_bf16_fp8 v110, v165, 1.0 op_sel:[1,0,0]
	v_dot2c_f32_bf16_e32 v119, v108, v220
	v_and_or_b32 v9, v3, s66, v230
	v_dot2c_f32_bf16_e32 v119, v110, v221
	global_load_dwordx4 v[162:165], v9, s[98:99]
	s_waitcnt lgkmcnt(0)
	s_waitcnt vmcnt(15)
	v_cvt_scalef32_pk_bf16_fp8 v104, v166, 1.0
	v_cvt_scalef32_pk_bf16_fp8 v106, v166, 1.0 op_sel:[1,0,0]
	v_dot2_f32_bf16 v120, v104, v214, 0
	v_cvt_scalef32_pk_bf16_fp8 v108, v167, 1.0
	v_dot2c_f32_bf16_e32 v120, v106, v215
	v_cvt_scalef32_pk_bf16_fp8 v110, v167, 1.0 op_sel:[1,0,0]
	v_dot2c_f32_bf16_e32 v120, v108, v216
	v_cvt_scalef32_pk_bf16_fp8 v104, v168, 1.0
	v_dot2c_f32_bf16_e32 v120, v110, v217
	v_cvt_scalef32_pk_bf16_fp8 v106, v168, 1.0 op_sel:[1,0,0]
	v_dot2c_f32_bf16_e32 v120, v104, v218
	v_cvt_scalef32_pk_bf16_fp8 v108, v169, 1.0
	v_dot2c_f32_bf16_e32 v120, v106, v219
	v_cvt_scalef32_pk_bf16_fp8 v110, v169, 1.0 op_sel:[1,0,0]
	v_dot2c_f32_bf16_e32 v120, v108, v220
	v_and_or_b32 v8, v4, s66, v230
	v_dot2c_f32_bf16_e32 v120, v110, v221
	global_load_dwordx4 v[166:169], v8, s[98:99]
	s_waitcnt vmcnt(15)
	v_cvt_scalef32_pk_bf16_fp8 v104, v170, 1.0
	v_cvt_scalef32_pk_bf16_fp8 v106, v170, 1.0 op_sel:[1,0,0]
	v_dot2_f32_bf16 v121, v104, v214, 0
	v_cvt_scalef32_pk_bf16_fp8 v108, v171, 1.0
	v_dot2c_f32_bf16_e32 v121, v106, v215
	v_cvt_scalef32_pk_bf16_fp8 v110, v171, 1.0 op_sel:[1,0,0]
	v_dot2c_f32_bf16_e32 v121, v108, v216
	v_cvt_scalef32_pk_bf16_fp8 v104, v172, 1.0
	v_dot2c_f32_bf16_e32 v121, v110, v217
	v_cvt_scalef32_pk_bf16_fp8 v106, v172, 1.0 op_sel:[1,0,0]
	v_dot2c_f32_bf16_e32 v121, v104, v218
	v_cvt_scalef32_pk_bf16_fp8 v108, v173, 1.0
	v_dot2c_f32_bf16_e32 v121, v106, v219
	v_cvt_scalef32_pk_bf16_fp8 v110, v173, 1.0 op_sel:[1,0,0]
	v_dot2c_f32_bf16_e32 v121, v108, v220
	v_and_or_b32 v9, v5, s66, v230
	v_dot2c_f32_bf16_e32 v121, v110, v221
	global_load_dwordx4 v[170:173], v9, s[98:99]
	ds_read_b128 v[0:3], v254 offset:32
	s_waitcnt vmcnt(15)
	v_cvt_scalef32_pk_bf16_fp8 v104, v174, 1.0
	v_cvt_scalef32_pk_bf16_fp8 v106, v174, 1.0 op_sel:[1,0,0]
	v_dot2_f32_bf16 v122, v104, v214, 0
	v_cvt_scalef32_pk_bf16_fp8 v108, v175, 1.0
	v_dot2c_f32_bf16_e32 v122, v106, v215
	v_cvt_scalef32_pk_bf16_fp8 v110, v175, 1.0 op_sel:[1,0,0]
	v_dot2c_f32_bf16_e32 v122, v108, v216
	v_cvt_scalef32_pk_bf16_fp8 v104, v176, 1.0
	v_dot2c_f32_bf16_e32 v122, v110, v217
	v_cvt_scalef32_pk_bf16_fp8 v106, v176, 1.0 op_sel:[1,0,0]
	v_dot2c_f32_bf16_e32 v122, v104, v218
	v_cvt_scalef32_pk_bf16_fp8 v108, v177, 1.0
	v_dot2c_f32_bf16_e32 v122, v106, v219
	v_cvt_scalef32_pk_bf16_fp8 v110, v177, 1.0 op_sel:[1,0,0]
	v_dot2c_f32_bf16_e32 v122, v108, v220
	v_and_or_b32 v8, v6, s66, v230
	v_dot2c_f32_bf16_e32 v122, v110, v221
	global_load_dwordx4 v[174:177], v8, s[98:99]
	s_waitcnt vmcnt(15)
; __device__ void phase_gather(const P& p, int vb, int nvb, char* smem) {
;     ...
;     for (int b0 = 0; b0 < 128; b0 += 8) {
;       float dp[8];
; #pragma unroll
;       for (int u = 0; u < 8; u++) {
;         const uint32_t key = mykl[b0 + u];
;         const int e = (int)(key >> 7);
;         const uint4* up = (const uint4*)(U + (size_t)e * 1024 + 16 * j);
;         uint4 uu[4];
; #pragma unroll
;         for (int i = 0; i < 4; i++) uu[i] = up[i * 16];
;         f32x2 d2 = f32x2{0.f, 0.f};
; #pragma unroll
;         for (int i = 0; i < 4; i++) {
;           const uint32_t w[4] = {uu[i].x, uu[i].y, uu[i].z, uu[i].w};
; #pragma unroll
;           for (int q = 0; q < 4; q++) {
;             d2 += __builtin_amdgcn_cvt_pk_f32_fp8((int)w[q], false) * xf[i * 8 + q * 2 + 0];
;             d2 += __builtin_amdgcn_cvt_pk_f32_fp8((int)w[q], true) * xf[i * 8 + q * 2 + 1];
;           }
;         }
;         dp[u] = d2.x + d2.y;
;       }
;       const bool h8 = (j & 8) != 0, h4 = (j & 4) != 0, h2b = (j & 2) != 0;
;       float q4[4], q2[2];
; #pragma unroll
;       for (int k = 0; k < 4; k++) { const float snd = h8 ? dp[k] : dp[k + 4], kp = h8 ? dp[k + 4] : dp[k]; q4[k] = kp + __shfl_xor(snd, 8); }
; #pragma unroll
;       for (int k = 0; k < 2; k++) { const float snd = h4 ? q4[k] : q4[k + 2], kp = h4 ? q4[k + 2] : q4[k]; q2[k] = kp + __shfl_xor(snd, 4); }
;       const float snd1 = h2b ? q2[0] : q2[1], kp1 = h2b ? q2[1] : q2[0];
;       float q1 = kp1 + __shfl_xor(snd1, 2);
;       q1 += __shfl_xor(q1, 1);
;       if ((j & 1) == 0) mywl[b0 + (j >> 1)] = q1;
	v_cvt_scalef32_pk_bf16_fp8 v104, v178, 1.0
	v_cvt_scalef32_pk_bf16_fp8 v106, v178, 1.0 op_sel:[1,0,0]
	v_dot2_f32_bf16 v123, v104, v214, 0
	v_cvt_scalef32_pk_bf16_fp8 v108, v179, 1.0
	v_dot2c_f32_bf16_e32 v123, v106, v215
	v_cvt_scalef32_pk_bf16_fp8 v110, v179, 1.0 op_sel:[1,0,0]
	v_dot2c_f32_bf16_e32 v123, v108, v216
	v_cvt_scalef32_pk_bf16_fp8 v104, v180, 1.0
	v_dot2c_f32_bf16_e32 v123, v110, v217
	v_cvt_scalef32_pk_bf16_fp8 v106, v180, 1.0 op_sel:[1,0,0]
	v_dot2c_f32_bf16_e32 v123, v104, v218
	v_cvt_scalef32_pk_bf16_fp8 v108, v181, 1.0
	v_dot2c_f32_bf16_e32 v123, v106, v219
	v_cvt_scalef32_pk_bf16_fp8 v110, v181, 1.0 op_sel:[1,0,0]
	v_dot2c_f32_bf16_e32 v123, v108, v220
	v_and_or_b32 v9, v7, s66, v230
	v_dot2c_f32_bf16_e32 v123, v110, v221
	global_load_dwordx4 v[178:181], v9, s[98:99]
	s_nop 2
	v_add_f32_dpp v10, v116, v116 row_ror:8 row_mask:0xf bank_mask:0x3
	v_add_f32_dpp v11, v117, v117 row_ror:8 row_mask:0xf bank_mask:0x3
	v_add_f32_dpp v12, v118, v118 row_ror:8 row_mask:0xf bank_mask:0x3
	v_add_f32_dpp v124, v119, v119 row_ror:8 row_mask:0xf bank_mask:0x3
	v_add_f32_dpp v10, v120, v120 row_ror:8 row_mask:0xf bank_mask:0xc
	v_add_f32_dpp v11, v121, v121 row_ror:8 row_mask:0xf bank_mask:0xc
	v_add_f32_dpp v12, v122, v122 row_ror:8 row_mask:0xf bank_mask:0xc
	v_add_f32_dpp v124, v123, v123 row_ror:8 row_mask:0xf bank_mask:0xc
	s_nop 0
	v_add_f32_dpp v125, v10, v10 row_shl:4 row_mask:0xf bank_mask:0x5
	v_add_f32_dpp v246, v11, v11 row_shl:4 row_mask:0xf bank_mask:0x5
	v_add_f32_dpp v125, v12, v12 row_shr:4 row_mask:0xf bank_mask:0xa
	v_add_f32_dpp v246, v124, v124 row_shr:4 row_mask:0xf bank_mask:0xa
	s_nop 1
	v_add_f32_dpp v247, v125, v125 quad_perm:[2,3,0,1] row_mask:0xf bank_mask:0xf
	v_add_f32_dpp v249, v246, v246 quad_perm:[2,3,0,1] row_mask:0xf bank_mask:0xf
	s_nop 0
	v_cndmask_b32_e64 v252, v249, v247, s[2:3]
	s_nop 1
	v_add_f32_dpp v253, v252, v252 quad_perm:[1,0,3,2] row_mask:0xf bank_mask:0xf
	s_and_saveexec_b64 s[20:21], s[4:5]
	ds_add_f32 v251, v253 offset:2048
	s_mov_b64 exec, s[20:21]
	s_waitcnt lgkmcnt(0)
	s_waitcnt vmcnt(15)
	v_cvt_scalef32_pk_bf16_fp8 v104, v182, 1.0
	v_cvt_scalef32_pk_bf16_fp8 v106, v182, 1.0 op_sel:[1,0,0]
	v_dot2_f32_bf16 v116, v104, v214, 0
	v_cvt_scalef32_pk_bf16_fp8 v108, v183, 1.0
	v_dot2c_f32_bf16_e32 v116, v106, v215
	v_cvt_scalef32_pk_bf16_fp8 v110, v183, 1.0 op_sel:[1,0,0]
	v_dot2c_f32_bf16_e32 v116, v108, v216
	v_cvt_scalef32_pk_bf16_fp8 v104, v184, 1.0
	v_dot2c_f32_bf16_e32 v116, v110, v217
	v_cvt_scalef32_pk_bf16_fp8 v106, v184, 1.0 op_sel:[1,0,0]
	v_dot2c_f32_bf16_e32 v116, v104, v218
	v_cvt_scalef32_pk_bf16_fp8 v108, v185, 1.0
	v_dot2c_f32_bf16_e32 v116, v106, v219
	v_cvt_scalef32_pk_bf16_fp8 v110, v185, 1.0 op_sel:[1,0,0]
	v_dot2c_f32_bf16_e32 v116, v108, v220
	v_and_or_b32 v8, v0, s66, v230
	v_dot2c_f32_bf16_e32 v116, v110, v221
	global_load_dwordx4 v[182:185], v8, s[98:99]
	s_waitcnt vmcnt(15)
	v_cvt_scalef32_pk_bf16_fp8 v104, v186, 1.0
	v_cvt_scalef32_pk_bf16_fp8 v106, v186, 1.0 op_sel:[1,0,0]
	v_dot2_f32_bf16 v117, v104, v214, 0
	v_cvt_scalef32_pk_bf16_fp8 v108, v187, 1.0
	v_dot2c_f32_bf16_e32 v117, v106, v215
	v_cvt_scalef32_pk_bf16_fp8 v110, v187, 1.0 op_sel:[1,0,0]
	v_dot2c_f32_bf16_e32 v117, v108, v216
	v_cvt_scalef32_pk_bf16_fp8 v104, v188, 1.0
	v_dot2c_f32_bf16_e32 v117, v110, v217
	v_cvt_scalef32_pk_bf16_fp8 v106, v188, 1.0 op_sel:[1,0,0]
	v_dot2c_f32_bf16_e32 v117, v104, v218
	v_cvt_scalef32_pk_bf16_fp8 v108, v189, 1.0
	v_dot2c_f32_bf16_e32 v117, v106, v219
	v_cvt_scalef32_pk_bf16_fp8 v110, v189, 1.0 op_sel:[1,0,0]
	v_dot2c_f32_bf16_e32 v117, v108, v220
	v_and_or_b32 v9, v1, s66, v230
	v_dot2c_f32_bf16_e32 v117, v110, v221
	global_load_dwordx4 v[186:189], v9, s[98:99]
	ds_read_b128 v[4:7], v254 offset:48
	s_waitcnt vmcnt(15)
	v_cvt_scalef32_pk_bf16_fp8 v104, v190, 1.0
	v_cvt_scalef32_pk_bf16_fp8 v106, v190, 1.0 op_sel:[1,0,0]
	v_dot2_f32_bf16 v118, v104, v214, 0
	v_cvt_scalef32_pk_bf16_fp8 v108, v191, 1.0
	v_dot2c_f32_bf16_e32 v118, v106, v215
	v_cvt_scalef32_pk_bf16_fp8 v110, v191, 1.0 op_sel:[1,0,0]
	v_dot2c_f32_bf16_e32 v118, v108, v216
	v_cvt_scalef32_pk_bf16_fp8 v104, v192, 1.0
	v_dot2c_f32_bf16_e32 v118, v110, v217
	v_cvt_scalef32_pk_bf16_fp8 v106, v192, 1.0 op_sel:[1,0,0]
	v_dot2c_f32_bf16_e32 v118, v104, v218
	v_cvt_scalef32_pk_bf16_fp8 v108, v193, 1.0
	v_dot2c_f32_bf16_e32 v118, v106, v219
	v_cvt_scalef32_pk_bf16_fp8 v110, v193, 1.0 op_sel:[1,0,0]
	v_dot2c_f32_bf16_e32 v118, v108, v220
	v_and_or_b32 v8, v2, s66, v230
	v_dot2c_f32_bf16_e32 v118, v110, v221
	global_load_dwordx4 v[190:193], v8, s[98:99]
	s_waitcnt vmcnt(15)
	v_cvt_scalef32_pk_bf16_fp8 v104, v194, 1.0
	v_cvt_scalef32_pk_bf16_fp8 v106, v194, 1.0 op_sel:[1,0,0]
	v_dot2_f32_bf16 v119, v104, v214, 0
	v_cvt_scalef32_pk_bf16_fp8 v108, v195, 1.0
	v_dot2c_f32_bf16_e32 v119, v106, v215
	v_cvt_scalef32_pk_bf16_fp8 v110, v195, 1.0 op_sel:[1,0,0]
	v_dot2c_f32_bf16_e32 v119, v108, v216
	v_cvt_scalef32_pk_bf16_fp8 v104, v196, 1.0
	v_dot2c_f32_bf16_e32 v119, v110, v217
	v_cvt_scalef32_pk_bf16_fp8 v106, v196, 1.0 op_sel:[1,0,0]
	v_dot2c_f32_bf16_e32 v119, v104, v218
	v_cvt_scalef32_pk_bf16_fp8 v108, v197, 1.0
	v_dot2c_f32_bf16_e32 v119, v106, v219
	v_cvt_scalef32_pk_bf16_fp8 v110, v197, 1.0 op_sel:[1,0,0]
	v_dot2c_f32_bf16_e32 v119, v108, v220
	v_and_or_b32 v9, v3, s66, v230
	v_dot2c_f32_bf16_e32 v119, v110, v221
	global_load_dwordx4 v[194:197], v9, s[98:99]
	s_waitcnt lgkmcnt(0)
	s_waitcnt vmcnt(15)
; __device__ void phase_gather(const P& p, int vb, int nvb, char* smem) {
;     ...
;     for (int b0 = 0; b0 < 128; b0 += 8) {
;       float dp[8];
; #pragma unroll
;       for (int u = 0; u < 8; u++) {
;         const uint32_t key = mykl[b0 + u];
;         const int e = (int)(key >> 7);
;         const uint4* up = (const uint4*)(U + (size_t)e * 1024 + 16 * j);
;         uint4 uu[4];
; #pragma unroll
;         for (int i = 0; i < 4; i++) uu[i] = up[i * 16];
;         f32x2 d2 = f32x2{0.f, 0.f};
; #pragma unroll
;         for (int i = 0; i < 4; i++) {
;           const uint32_t w[4] = {uu[i].x, uu[i].y, uu[i].z, uu[i].w};
; #pragma unroll
;           for (int q = 0; q < 4; q++) {
;             d2 += __builtin_amdgcn_cvt_pk_f32_fp8((int)w[q], false) * xf[i * 8 + q * 2 + 0];
;             d2 += __builtin_amdgcn_cvt_pk_f32_fp8((int)w[q], true) * xf[i * 8 + q * 2 + 1];
;           }
;         }
;         dp[u] = d2.x + d2.y;
;       }
;       const bool h8 = (j & 8) != 0, h4 = (j & 4) != 0, h2b = (j & 2) != 0;
;       float q4[4], q2[2];
; #pragma unroll
;       for (int k = 0; k < 4; k++) { const float snd = h8 ? dp[k] : dp[k + 4], kp = h8 ? dp[k + 4] : dp[k]; q4[k] = kp + __shfl_xor(snd, 8); }
; #pragma unroll
;       for (int k = 0; k < 2; k++) { const float snd = h4 ? q4[k] : q4[k + 2], kp = h4 ? q4[k + 2] : q4[k]; q2[k] = kp + __shfl_xor(snd, 4); }
;       const float snd1 = h2b ? q2[0] : q2[1], kp1 = h2b ? q2[1] : q2[0];
;       float q1 = kp1 + __shfl_xor(snd1, 2);
;       q1 += __shfl_xor(q1, 1);
;       if ((j & 1) == 0) mywl[b0 + (j >> 1)] = q1;
	v_cvt_scalef32_pk_bf16_fp8 v104, v198, 1.0
	v_cvt_scalef32_pk_bf16_fp8 v106, v198, 1.0 op_sel:[1,0,0]
	v_dot2_f32_bf16 v120, v104, v214, 0
	v_cvt_scalef32_pk_bf16_fp8 v108, v199, 1.0
	v_dot2c_f32_bf16_e32 v120, v106, v215
	v_cvt_scalef32_pk_bf16_fp8 v110, v199, 1.0 op_sel:[1,0,0]
	v_dot2c_f32_bf16_e32 v120, v108, v216
	v_cvt_scalef32_pk_bf16_fp8 v104, v200, 1.0
	v_dot2c_f32_bf16_e32 v120, v110, v217
	v_cvt_scalef32_pk_bf16_fp8 v106, v200, 1.0 op_sel:[1,0,0]
	v_dot2c_f32_bf16_e32 v120, v104, v218
	v_cvt_scalef32_pk_bf16_fp8 v108, v201, 1.0
	v_dot2c_f32_bf16_e32 v120, v106, v219
	v_cvt_scalef32_pk_bf16_fp8 v110, v201, 1.0 op_sel:[1,0,0]
	v_dot2c_f32_bf16_e32 v120, v108, v220
	v_and_or_b32 v8, v4, s66, v230
	v_dot2c_f32_bf16_e32 v120, v110, v221
	global_load_dwordx4 v[198:201], v8, s[98:99]
	s_add_i32 s27, s26, 2
	s_and_b32 s27, s27, 7
	s_lshl_b32 s27, s27, 6
	v_add_u32_e32 v254, s27, v133
	s_waitcnt vmcnt(15)
	v_cvt_scalef32_pk_bf16_fp8 v104, v202, 1.0
	v_cvt_scalef32_pk_bf16_fp8 v106, v202, 1.0 op_sel:[1,0,0]
	v_dot2_f32_bf16 v121, v104, v214, 0
	v_cvt_scalef32_pk_bf16_fp8 v108, v203, 1.0
	v_dot2c_f32_bf16_e32 v121, v106, v215
	v_cvt_scalef32_pk_bf16_fp8 v110, v203, 1.0 op_sel:[1,0,0]
	v_dot2c_f32_bf16_e32 v121, v108, v216
	v_cvt_scalef32_pk_bf16_fp8 v104, v204, 1.0
	v_dot2c_f32_bf16_e32 v121, v110, v217
	v_cvt_scalef32_pk_bf16_fp8 v106, v204, 1.0 op_sel:[1,0,0]
	v_dot2c_f32_bf16_e32 v121, v104, v218
	v_cvt_scalef32_pk_bf16_fp8 v108, v205, 1.0
	v_dot2c_f32_bf16_e32 v121, v106, v219
	v_cvt_scalef32_pk_bf16_fp8 v110, v205, 1.0 op_sel:[1,0,0]
	v_dot2c_f32_bf16_e32 v121, v108, v220
	v_and_or_b32 v9, v5, s66, v230
	v_dot2c_f32_bf16_e32 v121, v110, v221
	global_load_dwordx4 v[202:205], v9, s[98:99]
	ds_read_b128 v[0:3], v254
	s_waitcnt vmcnt(15)
	v_cvt_scalef32_pk_bf16_fp8 v104, v206, 1.0
	v_cvt_scalef32_pk_bf16_fp8 v106, v206, 1.0 op_sel:[1,0,0]
	v_dot2_f32_bf16 v122, v104, v214, 0
	v_cvt_scalef32_pk_bf16_fp8 v108, v207, 1.0
	v_dot2c_f32_bf16_e32 v122, v106, v215
	v_cvt_scalef32_pk_bf16_fp8 v110, v207, 1.0 op_sel:[1,0,0]
	v_dot2c_f32_bf16_e32 v122, v108, v216
	v_cvt_scalef32_pk_bf16_fp8 v104, v208, 1.0
	v_dot2c_f32_bf16_e32 v122, v110, v217
	v_cvt_scalef32_pk_bf16_fp8 v106, v208, 1.0 op_sel:[1,0,0]
	v_dot2c_f32_bf16_e32 v122, v104, v218
	v_cvt_scalef32_pk_bf16_fp8 v108, v209, 1.0
	v_dot2c_f32_bf16_e32 v122, v106, v219
	v_cvt_scalef32_pk_bf16_fp8 v110, v209, 1.0 op_sel:[1,0,0]
	v_dot2c_f32_bf16_e32 v122, v108, v220
	v_and_or_b32 v8, v6, s66, v230
	v_dot2c_f32_bf16_e32 v122, v110, v221
	global_load_dwordx4 v[206:209], v8, s[98:99]
	s_waitcnt vmcnt(15)
	v_cvt_scalef32_pk_bf16_fp8 v104, v210, 1.0
	v_cvt_scalef32_pk_bf16_fp8 v106, v210, 1.0 op_sel:[1,0,0]
	v_dot2_f32_bf16 v123, v104, v214, 0
	v_cvt_scalef32_pk_bf16_fp8 v108, v211, 1.0
	v_dot2c_f32_bf16_e32 v123, v106, v215
	v_cvt_scalef32_pk_bf16_fp8 v110, v211, 1.0 op_sel:[1,0,0]
	v_dot2c_f32_bf16_e32 v123, v108, v216
	v_cvt_scalef32_pk_bf16_fp8 v104, v212, 1.0
	v_dot2c_f32_bf16_e32 v123, v110, v217
	v_cvt_scalef32_pk_bf16_fp8 v106, v212, 1.0 op_sel:[1,0,0]
	v_dot2c_f32_bf16_e32 v123, v104, v218
	v_cvt_scalef32_pk_bf16_fp8 v108, v213, 1.0
	v_dot2c_f32_bf16_e32 v123, v106, v219
	v_cvt_scalef32_pk_bf16_fp8 v110, v213, 1.0 op_sel:[1,0,0]
	v_dot2c_f32_bf16_e32 v123, v108, v220
	v_and_or_b32 v9, v7, s66, v230
	v_dot2c_f32_bf16_e32 v123, v110, v221
	global_load_dwordx4 v[210:213], v9, s[98:99]
	s_nop 2
	v_add_f32_dpp v10, v116, v116 row_ror:8 row_mask:0xf bank_mask:0x3
	v_add_f32_dpp v11, v117, v117 row_ror:8 row_mask:0xf bank_mask:0x3
	v_add_f32_dpp v12, v118, v118 row_ror:8 row_mask:0xf bank_mask:0x3
	v_add_f32_dpp v124, v119, v119 row_ror:8 row_mask:0xf bank_mask:0x3
	v_add_f32_dpp v10, v120, v120 row_ror:8 row_mask:0xf bank_mask:0xc
	v_add_f32_dpp v11, v121, v121 row_ror:8 row_mask:0xf bank_mask:0xc
	v_add_f32_dpp v12, v122, v122 row_ror:8 row_mask:0xf bank_mask:0xc
	v_add_f32_dpp v124, v123, v123 row_ror:8 row_mask:0xf bank_mask:0xc
	s_nop 0
	v_add_f32_dpp v125, v10, v10 row_shl:4 row_mask:0xf bank_mask:0x5
	v_add_f32_dpp v246, v11, v11 row_shl:4 row_mask:0xf bank_mask:0x5
	v_add_f32_dpp v125, v12, v12 row_shr:4 row_mask:0xf bank_mask:0xa
	v_add_f32_dpp v246, v124, v124 row_shr:4 row_mask:0xf bank_mask:0xa
	s_nop 1
	v_add_f32_dpp v247, v125, v125 quad_perm:[2,3,0,1] row_mask:0xf bank_mask:0xf
	v_add_f32_dpp v249, v246, v246 quad_perm:[2,3,0,1] row_mask:0xf bank_mask:0xf
	s_nop 0
	v_cndmask_b32_e64 v252, v249, v247, s[2:3]
	s_nop 1
	v_add_f32_dpp v253, v252, v252 quad_perm:[1,0,3,2] row_mask:0xf bank_mask:0xf
	s_and_saveexec_b64 s[20:21], s[4:5]
	ds_add_f32 v251, v253 offset:2080
	s_mov_b64 exec, s[20:21]
	s_add_i32 s26, s26, 1
	s_add_i32 s20, s26, 1
	s_lshr_b32 s27, s20, 3
	s_and_b32 s27, s27, 3
	s_lshl_b32 s27, s27, 22
	v_add_u32_e32 v230, s27, v250
	s_and_b32 s27, s26, 7
	s_lshl_b32 s27, s27, 6
	v_add_u32_e32 v251, s27, v231
	s_branch .Lgu_iter
; __device__ void phase_gather(const P& p, int vb, int nvb, char* smem) {
;     ...
;     for (int b0 = 0; b0 < 128; b0 += 8) {
;       float dp[8];
; #pragma unroll
;       for (int u = 0; u < 8; u++) {
;         const uint32_t key = mykl[b0 + u];
;         const int e = (int)(key >> 7);
;         const uint4* up = (const uint4*)(U + (size_t)e * 1024 + 16 * j);
;         uint4 uu[4];
; #pragma unroll
;         for (int i = 0; i < 4; i++) uu[i] = up[i * 16];
;         f32x2 d2 = f32x2{0.f, 0.f};
; #pragma unroll
;         for (int i = 0; i < 4; i++) {
;           const uint32_t w[4] = {uu[i].x, uu[i].y, uu[i].z, uu[i].w};
; #pragma unroll
;           for (int q = 0; q < 4; q++) {
;             d2 += __builtin_amdgcn_cvt_pk_f32_fp8((int)w[q], false) * xf[i * 8 + q * 2 + 0];
;             d2 += __builtin_amdgcn_cvt_pk_f32_fp8((int)w[q], true) * xf[i * 8 + q * 2 + 1];
;           }
;         }
;         dp[u] = d2.x + d2.y;
;       }
;       const bool h8 = (j & 8) != 0, h4 = (j & 4) != 0, h2b = (j & 2) != 0;
;       float q4[4], q2[2];
; #pragma unroll
;       for (int k = 0; k < 4; k++) { const float snd = h8 ? dp[k] : dp[k + 4], kp = h8 ? dp[k + 4] : dp[k]; q4[k] = kp + __shfl_xor(snd, 8); }
; #pragma unroll
;       for (int k = 0; k < 2; k++) { const float snd = h4 ? q4[k] : q4[k + 2], kp = h4 ? q4[k + 2] : q4[k]; q2[k] = kp + __shfl_xor(snd, 4); }
;       const float snd1 = h2b ? q2[0] : q2[1], kp1 = h2b ? q2[1] : q2[0];
;       float q1 = kp1 + __shfl_xor(snd1, 2);
;       q1 += __shfl_xor(q1, 1);
;       if ((j & 1) == 0) mywl[b0 + (j >> 1)] = q1;
.Lgu_last:
	s_waitcnt vmcnt(15)
	v_cvt_scalef32_pk_bf16_fp8 v104, v150, 1.0
	v_cvt_scalef32_pk_bf16_fp8 v106, v150, 1.0 op_sel:[1,0,0]
	v_dot2_f32_bf16 v116, v104, v214, 0
	v_cvt_scalef32_pk_bf16_fp8 v108, v151, 1.0
	v_dot2c_f32_bf16_e32 v116, v106, v215
	v_cvt_scalef32_pk_bf16_fp8 v110, v151, 1.0 op_sel:[1,0,0]
	v_dot2c_f32_bf16_e32 v116, v108, v216
	v_cvt_scalef32_pk_bf16_fp8 v104, v152, 1.0
	v_dot2c_f32_bf16_e32 v116, v110, v217
	v_cvt_scalef32_pk_bf16_fp8 v106, v152, 1.0 op_sel:[1,0,0]
	v_dot2c_f32_bf16_e32 v116, v104, v218
	v_cvt_scalef32_pk_bf16_fp8 v108, v153, 1.0
	v_dot2c_f32_bf16_e32 v116, v106, v219
	v_cvt_scalef32_pk_bf16_fp8 v110, v153, 1.0 op_sel:[1,0,0]
	v_dot2c_f32_bf16_e32 v116, v108, v220
	s_nop 0
	v_dot2c_f32_bf16_e32 v116, v110, v221
	s_waitcnt vmcnt(14)
	v_cvt_scalef32_pk_bf16_fp8 v104, v154, 1.0
	v_cvt_scalef32_pk_bf16_fp8 v106, v154, 1.0 op_sel:[1,0,0]
	v_dot2_f32_bf16 v117, v104, v214, 0
	v_cvt_scalef32_pk_bf16_fp8 v108, v155, 1.0
	v_dot2c_f32_bf16_e32 v117, v106, v215
	v_cvt_scalef32_pk_bf16_fp8 v110, v155, 1.0 op_sel:[1,0,0]
	v_dot2c_f32_bf16_e32 v117, v108, v216
	v_cvt_scalef32_pk_bf16_fp8 v104, v156, 1.0
	v_dot2c_f32_bf16_e32 v117, v110, v217
	v_cvt_scalef32_pk_bf16_fp8 v106, v156, 1.0 op_sel:[1,0,0]
	v_dot2c_f32_bf16_e32 v117, v104, v218
	v_cvt_scalef32_pk_bf16_fp8 v108, v157, 1.0
	v_dot2c_f32_bf16_e32 v117, v106, v219
	v_cvt_scalef32_pk_bf16_fp8 v110, v157, 1.0 op_sel:[1,0,0]
	v_dot2c_f32_bf16_e32 v117, v108, v220
	s_nop 0
	v_dot2c_f32_bf16_e32 v117, v110, v221
	s_waitcnt vmcnt(13)
	v_cvt_scalef32_pk_bf16_fp8 v104, v158, 1.0
	v_cvt_scalef32_pk_bf16_fp8 v106, v158, 1.0 op_sel:[1,0,0]
	v_dot2_f32_bf16 v118, v104, v214, 0
	v_cvt_scalef32_pk_bf16_fp8 v108, v159, 1.0
	v_dot2c_f32_bf16_e32 v118, v106, v215
	v_cvt_scalef32_pk_bf16_fp8 v110, v159, 1.0 op_sel:[1,0,0]
	v_dot2c_f32_bf16_e32 v118, v108, v216
	v_cvt_scalef32_pk_bf16_fp8 v104, v160, 1.0
	v_dot2c_f32_bf16_e32 v118, v110, v217
	v_cvt_scalef32_pk_bf16_fp8 v106, v160, 1.0 op_sel:[1,0,0]
	v_dot2c_f32_bf16_e32 v118, v104, v218
	v_cvt_scalef32_pk_bf16_fp8 v108, v161, 1.0
	v_dot2c_f32_bf16_e32 v118, v106, v219
	v_cvt_scalef32_pk_bf16_fp8 v110, v161, 1.0 op_sel:[1,0,0]
	v_dot2c_f32_bf16_e32 v118, v108, v220
	s_nop 0
	v_dot2c_f32_bf16_e32 v118, v110, v221
	s_waitcnt vmcnt(12)
	v_cvt_scalef32_pk_bf16_fp8 v104, v162, 1.0
	v_cvt_scalef32_pk_bf16_fp8 v106, v162, 1.0 op_sel:[1,0,0]
	v_dot2_f32_bf16 v119, v104, v214, 0
	v_cvt_scalef32_pk_bf16_fp8 v108, v163, 1.0
	v_dot2c_f32_bf16_e32 v119, v106, v215
	v_cvt_scalef32_pk_bf16_fp8 v110, v163, 1.0 op_sel:[1,0,0]
	v_dot2c_f32_bf16_e32 v119, v108, v216
	v_cvt_scalef32_pk_bf16_fp8 v104, v164, 1.0
	v_dot2c_f32_bf16_e32 v119, v110, v217
	v_cvt_scalef32_pk_bf16_fp8 v106, v164, 1.0 op_sel:[1,0,0]
	v_dot2c_f32_bf16_e32 v119, v104, v218
	v_cvt_scalef32_pk_bf16_fp8 v108, v165, 1.0
	v_dot2c_f32_bf16_e32 v119, v106, v219
	v_cvt_scalef32_pk_bf16_fp8 v110, v165, 1.0 op_sel:[1,0,0]
	v_dot2c_f32_bf16_e32 v119, v108, v220
	s_nop 0
	v_dot2c_f32_bf16_e32 v119, v110, v221
	s_waitcnt vmcnt(11)
	v_cvt_scalef32_pk_bf16_fp8 v104, v166, 1.0
	v_cvt_scalef32_pk_bf16_fp8 v106, v166, 1.0 op_sel:[1,0,0]
	v_dot2_f32_bf16 v120, v104, v214, 0
	v_cvt_scalef32_pk_bf16_fp8 v108, v167, 1.0
	v_dot2c_f32_bf16_e32 v120, v106, v215
	v_cvt_scalef32_pk_bf16_fp8 v110, v167, 1.0 op_sel:[1,0,0]
	v_dot2c_f32_bf16_e32 v120, v108, v216
	v_cvt_scalef32_pk_bf16_fp8 v104, v168, 1.0
	v_dot2c_f32_bf16_e32 v120, v110, v217
	v_cvt_scalef32_pk_bf16_fp8 v106, v168, 1.0 op_sel:[1,0,0]
	v_dot2c_f32_bf16_e32 v120, v104, v218
	v_cvt_scalef32_pk_bf16_fp8 v108, v169, 1.0
	v_dot2c_f32_bf16_e32 v120, v106, v219
	v_cvt_scalef32_pk_bf16_fp8 v110, v169, 1.0 op_sel:[1,0,0]
	v_dot2c_f32_bf16_e32 v120, v108, v220
	s_nop 0
	v_dot2c_f32_bf16_e32 v120, v110, v221
	s_waitcnt vmcnt(10)
	v_cvt_scalef32_pk_bf16_fp8 v104, v170, 1.0
	v_cvt_scalef32_pk_bf16_fp8 v106, v170, 1.0 op_sel:[1,0,0]
	v_dot2_f32_bf16 v121, v104, v214, 0
	v_cvt_scalef32_pk_bf16_fp8 v108, v171, 1.0
	v_dot2c_f32_bf16_e32 v121, v106, v215
	v_cvt_scalef32_pk_bf16_fp8 v110, v171, 1.0 op_sel:[1,0,0]
	v_dot2c_f32_bf16_e32 v121, v108, v216
	v_cvt_scalef32_pk_bf16_fp8 v104, v172, 1.0
	v_dot2c_f32_bf16_e32 v121, v110, v217
	v_cvt_scalef32_pk_bf16_fp8 v106, v172, 1.0 op_sel:[1,0,0]
	v_dot2c_f32_bf16_e32 v121, v104, v218
	v_cvt_scalef32_pk_bf16_fp8 v108, v173, 1.0
	v_dot2c_f32_bf16_e32 v121, v106, v219
	v_cvt_scalef32_pk_bf16_fp8 v110, v173, 1.0 op_sel:[1,0,0]
	v_dot2c_f32_bf16_e32 v121, v108, v220
	s_nop 0
	v_dot2c_f32_bf16_e32 v121, v110, v221
	s_waitcnt vmcnt(9)
	v_cvt_scalef32_pk_bf16_fp8 v104, v174, 1.0
	v_cvt_scalef32_pk_bf16_fp8 v106, v174, 1.0 op_sel:[1,0,0]
	v_dot2_f32_bf16 v122, v104, v214, 0
	v_cvt_scalef32_pk_bf16_fp8 v108, v175, 1.0
	v_dot2c_f32_bf16_e32 v122, v106, v215
	v_cvt_scalef32_pk_bf16_fp8 v110, v175, 1.0 op_sel:[1,0,0]
	v_dot2c_f32_bf16_e32 v122, v108, v216
	v_cvt_scalef32_pk_bf16_fp8 v104, v176, 1.0
	v_dot2c_f32_bf16_e32 v122, v110, v217
	v_cvt_scalef32_pk_bf16_fp8 v106, v176, 1.0 op_sel:[1,0,0]
	v_dot2c_f32_bf16_e32 v122, v104, v218
	v_cvt_scalef32_pk_bf16_fp8 v108, v177, 1.0
	v_dot2c_f32_bf16_e32 v122, v106, v219
	v_cvt_scalef32_pk_bf16_fp8 v110, v177, 1.0 op_sel:[1,0,0]
	v_dot2c_f32_bf16_e32 v122, v108, v220
	s_nop 0
	v_dot2c_f32_bf16_e32 v122, v110, v221
	s_waitcnt vmcnt(8)
; __device__ void phase_gather(const P& p, int vb, int nvb, char* smem) {
;     ...
;     for (int b0 = 0; b0 < 128; b0 += 8) {
;       float dp[8];
; #pragma unroll
;       for (int u = 0; u < 8; u++) {
;         const uint32_t key = mykl[b0 + u];
;         const int e = (int)(key >> 7);
;         const uint4* up = (const uint4*)(U + (size_t)e * 1024 + 16 * j);
;         uint4 uu[4];
; #pragma unroll
;         for (int i = 0; i < 4; i++) uu[i] = up[i * 16];
;         f32x2 d2 = f32x2{0.f, 0.f};
; #pragma unroll
;         for (int i = 0; i < 4; i++) {
;           const uint32_t w[4] = {uu[i].x, uu[i].y, uu[i].z, uu[i].w};
; #pragma unroll
;           for (int q = 0; q < 4; q++) {
;             d2 += __builtin_amdgcn_cvt_pk_f32_fp8((int)w[q], false) * xf[i * 8 + q * 2 + 0];
;             d2 += __builtin_amdgcn_cvt_pk_f32_fp8((int)w[q], true) * xf[i * 8 + q * 2 + 1];
;           }
;         }
;         dp[u] = d2.x + d2.y;
;       }
;       const bool h8 = (j & 8) != 0, h4 = (j & 4) != 0, h2b = (j & 2) != 0;
;       float q4[4], q2[2];
; #pragma unroll
;       for (int k = 0; k < 4; k++) { const float snd = h8 ? dp[k] : dp[k + 4], kp = h8 ? dp[k + 4] : dp[k]; q4[k] = kp + __shfl_xor(snd, 8); }
; #pragma unroll
;       for (int k = 0; k < 2; k++) { const float snd = h4 ? q4[k] : q4[k + 2], kp = h4 ? q4[k + 2] : q4[k]; q2[k] = kp + __shfl_xor(snd, 4); }
;       const float snd1 = h2b ? q2[0] : q2[1], kp1 = h2b ? q2[1] : q2[0];
;       float q1 = kp1 + __shfl_xor(snd1, 2);
;       q1 += __shfl_xor(q1, 1);
;       if ((j & 1) == 0) mywl[b0 + (j >> 1)] = q1;
	v_cvt_scalef32_pk_bf16_fp8 v104, v178, 1.0
	v_cvt_scalef32_pk_bf16_fp8 v106, v178, 1.0 op_sel:[1,0,0]
	v_dot2_f32_bf16 v123, v104, v214, 0
	v_cvt_scalef32_pk_bf16_fp8 v108, v179, 1.0
	v_dot2c_f32_bf16_e32 v123, v106, v215
	v_cvt_scalef32_pk_bf16_fp8 v110, v179, 1.0 op_sel:[1,0,0]
	v_dot2c_f32_bf16_e32 v123, v108, v216
	v_cvt_scalef32_pk_bf16_fp8 v104, v180, 1.0
	v_dot2c_f32_bf16_e32 v123, v110, v217
	v_cvt_scalef32_pk_bf16_fp8 v106, v180, 1.0 op_sel:[1,0,0]
	v_dot2c_f32_bf16_e32 v123, v104, v218
	v_cvt_scalef32_pk_bf16_fp8 v108, v181, 1.0
	v_dot2c_f32_bf16_e32 v123, v106, v219
	v_cvt_scalef32_pk_bf16_fp8 v110, v181, 1.0 op_sel:[1,0,0]
	v_dot2c_f32_bf16_e32 v123, v108, v220
	s_nop 0
	v_dot2c_f32_bf16_e32 v123, v110, v221
	s_nop 2
	v_add_f32_dpp v10, v116, v116 row_ror:8 row_mask:0xf bank_mask:0x3
	v_add_f32_dpp v11, v117, v117 row_ror:8 row_mask:0xf bank_mask:0x3
	v_add_f32_dpp v12, v118, v118 row_ror:8 row_mask:0xf bank_mask:0x3
	v_add_f32_dpp v124, v119, v119 row_ror:8 row_mask:0xf bank_mask:0x3
	v_add_f32_dpp v10, v120, v120 row_ror:8 row_mask:0xf bank_mask:0xc
	v_add_f32_dpp v11, v121, v121 row_ror:8 row_mask:0xf bank_mask:0xc
	v_add_f32_dpp v12, v122, v122 row_ror:8 row_mask:0xf bank_mask:0xc
	v_add_f32_dpp v124, v123, v123 row_ror:8 row_mask:0xf bank_mask:0xc
	s_nop 0
	v_add_f32_dpp v125, v10, v10 row_shl:4 row_mask:0xf bank_mask:0x5
	v_add_f32_dpp v246, v11, v11 row_shl:4 row_mask:0xf bank_mask:0x5
	v_add_f32_dpp v125, v12, v12 row_shr:4 row_mask:0xf bank_mask:0xa
	v_add_f32_dpp v246, v124, v124 row_shr:4 row_mask:0xf bank_mask:0xa
	s_nop 1
	v_add_f32_dpp v247, v125, v125 quad_perm:[2,3,0,1] row_mask:0xf bank_mask:0xf
	v_add_f32_dpp v249, v246, v246 quad_perm:[2,3,0,1] row_mask:0xf bank_mask:0xf
	s_nop 0
	v_cndmask_b32_e64 v252, v249, v247, s[2:3]
	s_nop 1
	v_add_f32_dpp v253, v252, v252 quad_perm:[1,0,3,2] row_mask:0xf bank_mask:0xf
	s_and_saveexec_b64 s[20:21], s[4:5]
	ds_add_f32 v251, v253 offset:2048
	s_mov_b64 exec, s[20:21]
	s_waitcnt vmcnt(7)
	v_cvt_scalef32_pk_bf16_fp8 v104, v182, 1.0
	v_cvt_scalef32_pk_bf16_fp8 v106, v182, 1.0 op_sel:[1,0,0]
	v_dot2_f32_bf16 v116, v104, v214, 0
	v_cvt_scalef32_pk_bf16_fp8 v108, v183, 1.0
	v_dot2c_f32_bf16_e32 v116, v106, v215
	v_cvt_scalef32_pk_bf16_fp8 v110, v183, 1.0 op_sel:[1,0,0]
	v_dot2c_f32_bf16_e32 v116, v108, v216
	v_cvt_scalef32_pk_bf16_fp8 v104, v184, 1.0
	v_dot2c_f32_bf16_e32 v116, v110, v217
	v_cvt_scalef32_pk_bf16_fp8 v106, v184, 1.0 op_sel:[1,0,0]
	v_dot2c_f32_bf16_e32 v116, v104, v218
	v_cvt_scalef32_pk_bf16_fp8 v108, v185, 1.0
	v_dot2c_f32_bf16_e32 v116, v106, v219
	v_cvt_scalef32_pk_bf16_fp8 v110, v185, 1.0 op_sel:[1,0,0]
	v_dot2c_f32_bf16_e32 v116, v108, v220
	s_nop 0
	v_dot2c_f32_bf16_e32 v116, v110, v221
	s_waitcnt vmcnt(6)
	v_cvt_scalef32_pk_bf16_fp8 v104, v186, 1.0
	v_cvt_scalef32_pk_bf16_fp8 v106, v186, 1.0 op_sel:[1,0,0]
	v_dot2_f32_bf16 v117, v104, v214, 0
	v_cvt_scalef32_pk_bf16_fp8 v108, v187, 1.0
	v_dot2c_f32_bf16_e32 v117, v106, v215
	v_cvt_scalef32_pk_bf16_fp8 v110, v187, 1.0 op_sel:[1,0,0]
	v_dot2c_f32_bf16_e32 v117, v108, v216
	v_cvt_scalef32_pk_bf16_fp8 v104, v188, 1.0
	v_dot2c_f32_bf16_e32 v117, v110, v217
	v_cvt_scalef32_pk_bf16_fp8 v106, v188, 1.0 op_sel:[1,0,0]
	v_dot2c_f32_bf16_e32 v117, v104, v218
	v_cvt_scalef32_pk_bf16_fp8 v108, v189, 1.0
	v_dot2c_f32_bf16_e32 v117, v106, v219
	v_cvt_scalef32_pk_bf16_fp8 v110, v189, 1.0 op_sel:[1,0,0]
	v_dot2c_f32_bf16_e32 v117, v108, v220
	s_nop 0
	v_dot2c_f32_bf16_e32 v117, v110, v221
	s_waitcnt vmcnt(5)
	v_cvt_scalef32_pk_bf16_fp8 v104, v190, 1.0
	v_cvt_scalef32_pk_bf16_fp8 v106, v190, 1.0 op_sel:[1,0,0]
	v_dot2_f32_bf16 v118, v104, v214, 0
	v_cvt_scalef32_pk_bf16_fp8 v108, v191, 1.0
	v_dot2c_f32_bf16_e32 v118, v106, v215
	v_cvt_scalef32_pk_bf16_fp8 v110, v191, 1.0 op_sel:[1,0,0]
	v_dot2c_f32_bf16_e32 v118, v108, v216
	v_cvt_scalef32_pk_bf16_fp8 v104, v192, 1.0
	v_dot2c_f32_bf16_e32 v118, v110, v217
	v_cvt_scalef32_pk_bf16_fp8 v106, v192, 1.0 op_sel:[1,0,0]
	v_dot2c_f32_bf16_e32 v118, v104, v218
	v_cvt_scalef32_pk_bf16_fp8 v108, v193, 1.0
	v_dot2c_f32_bf16_e32 v118, v106, v219
	v_cvt_scalef32_pk_bf16_fp8 v110, v193, 1.0 op_sel:[1,0,0]
	v_dot2c_f32_bf16_e32 v118, v108, v220
	s_nop 0
	v_dot2c_f32_bf16_e32 v118, v110, v221
	s_waitcnt vmcnt(4)
; __device__ void phase_gather(const P& p, int vb, int nvb, char* smem) {
;     ...
;     for (int b0 = 0; b0 < 128; b0 += 8) {
;       float dp[8];
; #pragma unroll
;       for (int u = 0; u < 8; u++) {
;         const uint32_t key = mykl[b0 + u];
;         const int e = (int)(key >> 7);
;         const uint4* up = (const uint4*)(U + (size_t)e * 1024 + 16 * j);
;         uint4 uu[4];
; #pragma unroll
;         for (int i = 0; i < 4; i++) uu[i] = up[i * 16];
;         f32x2 d2 = f32x2{0.f, 0.f};
; #pragma unroll
;         for (int i = 0; i < 4; i++) {
;           const uint32_t w[4] = {uu[i].x, uu[i].y, uu[i].z, uu[i].w};
; #pragma unroll
;           for (int q = 0; q < 4; q++) {
;             d2 += __builtin_amdgcn_cvt_pk_f32_fp8((int)w[q], false) * xf[i * 8 + q * 2 + 0];
;             d2 += __builtin_amdgcn_cvt_pk_f32_fp8((int)w[q], true) * xf[i * 8 + q * 2 + 1];
;           }
;         }
;         dp[u] = d2.x + d2.y;
;       }
;       const bool h8 = (j & 8) != 0, h4 = (j & 4) != 0, h2b = (j & 2) != 0;
;       float q4[4], q2[2];
; #pragma unroll
;       for (int k = 0; k < 4; k++) { const float snd = h8 ? dp[k] : dp[k + 4], kp = h8 ? dp[k + 4] : dp[k]; q4[k] = kp + __shfl_xor(snd, 8); }
; #pragma unroll
;       for (int k = 0; k < 2; k++) { const float snd = h4 ? q4[k] : q4[k + 2], kp = h4 ? q4[k + 2] : q4[k]; q2[k] = kp + __shfl_xor(snd, 4); }
;       const float snd1 = h2b ? q2[0] : q2[1], kp1 = h2b ? q2[1] : q2[0];
;       float q1 = kp1 + __shfl_xor(snd1, 2);
;       q1 += __shfl_xor(q1, 1);
;       if ((j & 1) == 0) mywl[b0 + (j >> 1)] = q1;
	v_cvt_scalef32_pk_bf16_fp8 v104, v194, 1.0
	v_cvt_scalef32_pk_bf16_fp8 v106, v194, 1.0 op_sel:[1,0,0]
	v_dot2_f32_bf16 v119, v104, v214, 0
	v_cvt_scalef32_pk_bf16_fp8 v108, v195, 1.0
	v_dot2c_f32_bf16_e32 v119, v106, v215
	v_cvt_scalef32_pk_bf16_fp8 v110, v195, 1.0 op_sel:[1,0,0]
	v_dot2c_f32_bf16_e32 v119, v108, v216
	v_cvt_scalef32_pk_bf16_fp8 v104, v196, 1.0
	v_dot2c_f32_bf16_e32 v119, v110, v217
	v_cvt_scalef32_pk_bf16_fp8 v106, v196, 1.0 op_sel:[1,0,0]
	v_dot2c_f32_bf16_e32 v119, v104, v218
	v_cvt_scalef32_pk_bf16_fp8 v108, v197, 1.0
	v_dot2c_f32_bf16_e32 v119, v106, v219
	v_cvt_scalef32_pk_bf16_fp8 v110, v197, 1.0 op_sel:[1,0,0]
	v_dot2c_f32_bf16_e32 v119, v108, v220
	s_nop 0
	v_dot2c_f32_bf16_e32 v119, v110, v221
	s_waitcnt vmcnt(3)
	v_cvt_scalef32_pk_bf16_fp8 v104, v198, 1.0
	v_cvt_scalef32_pk_bf16_fp8 v106, v198, 1.0 op_sel:[1,0,0]
	v_dot2_f32_bf16 v120, v104, v214, 0
	v_cvt_scalef32_pk_bf16_fp8 v108, v199, 1.0
	v_dot2c_f32_bf16_e32 v120, v106, v215
	v_cvt_scalef32_pk_bf16_fp8 v110, v199, 1.0 op_sel:[1,0,0]
	v_dot2c_f32_bf16_e32 v120, v108, v216
	v_cvt_scalef32_pk_bf16_fp8 v104, v200, 1.0
	v_dot2c_f32_bf16_e32 v120, v110, v217
	v_cvt_scalef32_pk_bf16_fp8 v106, v200, 1.0 op_sel:[1,0,0]
	v_dot2c_f32_bf16_e32 v120, v104, v218
	v_cvt_scalef32_pk_bf16_fp8 v108, v201, 1.0
	v_dot2c_f32_bf16_e32 v120, v106, v219
	v_cvt_scalef32_pk_bf16_fp8 v110, v201, 1.0 op_sel:[1,0,0]
	v_dot2c_f32_bf16_e32 v120, v108, v220
	s_nop 0
	v_dot2c_f32_bf16_e32 v120, v110, v221
	s_waitcnt vmcnt(2)
	v_cvt_scalef32_pk_bf16_fp8 v104, v202, 1.0
	v_cvt_scalef32_pk_bf16_fp8 v106, v202, 1.0 op_sel:[1,0,0]
	v_dot2_f32_bf16 v121, v104, v214, 0
	v_cvt_scalef32_pk_bf16_fp8 v108, v203, 1.0
	v_dot2c_f32_bf16_e32 v121, v106, v215
	v_cvt_scalef32_pk_bf16_fp8 v110, v203, 1.0 op_sel:[1,0,0]
	v_dot2c_f32_bf16_e32 v121, v108, v216
	v_cvt_scalef32_pk_bf16_fp8 v104, v204, 1.0
	v_dot2c_f32_bf16_e32 v121, v110, v217
	v_cvt_scalef32_pk_bf16_fp8 v106, v204, 1.0 op_sel:[1,0,0]
	v_dot2c_f32_bf16_e32 v121, v104, v218
	v_cvt_scalef32_pk_bf16_fp8 v108, v205, 1.0
	v_dot2c_f32_bf16_e32 v121, v106, v219
	v_cvt_scalef32_pk_bf16_fp8 v110, v205, 1.0 op_sel:[1,0,0]
	v_dot2c_f32_bf16_e32 v121, v108, v220
	s_nop 0
	v_dot2c_f32_bf16_e32 v121, v110, v221
	s_waitcnt vmcnt(1)
	v_cvt_scalef32_pk_bf16_fp8 v104, v206, 1.0
	v_cvt_scalef32_pk_bf16_fp8 v106, v206, 1.0 op_sel:[1,0,0]
	v_dot2_f32_bf16 v122, v104, v214, 0
	v_cvt_scalef32_pk_bf16_fp8 v108, v207, 1.0
	v_dot2c_f32_bf16_e32 v122, v106, v215
	v_cvt_scalef32_pk_bf16_fp8 v110, v207, 1.0 op_sel:[1,0,0]
	v_dot2c_f32_bf16_e32 v122, v108, v216
	v_cvt_scalef32_pk_bf16_fp8 v104, v208, 1.0
	v_dot2c_f32_bf16_e32 v122, v110, v217
	v_cvt_scalef32_pk_bf16_fp8 v106, v208, 1.0 op_sel:[1,0,0]
	v_dot2c_f32_bf16_e32 v122, v104, v218
	v_cvt_scalef32_pk_bf16_fp8 v108, v209, 1.0
	v_dot2c_f32_bf16_e32 v122, v106, v219
	v_cvt_scalef32_pk_bf16_fp8 v110, v209, 1.0 op_sel:[1,0,0]
	v_dot2c_f32_bf16_e32 v122, v108, v220
	s_nop 0
	v_dot2c_f32_bf16_e32 v122, v110, v221
	s_waitcnt vmcnt(0)
	v_cvt_scalef32_pk_bf16_fp8 v104, v210, 1.0
	v_cvt_scalef32_pk_bf16_fp8 v106, v210, 1.0 op_sel:[1,0,0]
	v_dot2_f32_bf16 v123, v104, v214, 0
	v_cvt_scalef32_pk_bf16_fp8 v108, v211, 1.0
	v_dot2c_f32_bf16_e32 v123, v106, v215
	v_cvt_scalef32_pk_bf16_fp8 v110, v211, 1.0 op_sel:[1,0,0]
	v_dot2c_f32_bf16_e32 v123, v108, v216
	v_cvt_scalef32_pk_bf16_fp8 v104, v212, 1.0
	v_dot2c_f32_bf16_e32 v123, v110, v217
	v_cvt_scalef32_pk_bf16_fp8 v106, v212, 1.0 op_sel:[1,0,0]
	v_dot2c_f32_bf16_e32 v123, v104, v218
	v_cvt_scalef32_pk_bf16_fp8 v108, v213, 1.0
	v_dot2c_f32_bf16_e32 v123, v106, v219
	v_cvt_scalef32_pk_bf16_fp8 v110, v213, 1.0 op_sel:[1,0,0]
	v_dot2c_f32_bf16_e32 v123, v108, v220
	s_nop 0
	v_dot2c_f32_bf16_e32 v123, v110, v221
	s_nop 2
	v_add_f32_dpp v10, v116, v116 row_ror:8 row_mask:0xf bank_mask:0x3
	v_add_f32_dpp v11, v117, v117 row_ror:8 row_mask:0xf bank_mask:0x3
	v_add_f32_dpp v12, v118, v118 row_ror:8 row_mask:0xf bank_mask:0x3
	v_add_f32_dpp v124, v119, v119 row_ror:8 row_mask:0xf bank_mask:0x3
	v_add_f32_dpp v10, v120, v120 row_ror:8 row_mask:0xf bank_mask:0xc
	v_add_f32_dpp v11, v121, v121 row_ror:8 row_mask:0xf bank_mask:0xc
	v_add_f32_dpp v12, v122, v122 row_ror:8 row_mask:0xf bank_mask:0xc
	v_add_f32_dpp v124, v123, v123 row_ror:8 row_mask:0xf bank_mask:0xc
	s_nop 0
	v_add_f32_dpp v125, v10, v10 row_shl:4 row_mask:0xf bank_mask:0x5
	v_add_f32_dpp v246, v11, v11 row_shl:4 row_mask:0xf bank_mask:0x5
	v_add_f32_dpp v125, v12, v12 row_shr:4 row_mask:0xf bank_mask:0xa
	v_add_f32_dpp v246, v124, v124 row_shr:4 row_mask:0xf bank_mask:0xa
	s_nop 1
	v_add_f32_dpp v247, v125, v125 quad_perm:[2,3,0,1] row_mask:0xf bank_mask:0xf
	v_add_f32_dpp v249, v246, v246 quad_perm:[2,3,0,1] row_mask:0xf bank_mask:0xf
	s_nop 0
	v_cndmask_b32_e64 v252, v249, v247, s[2:3]
	s_nop 1
	v_add_f32_dpp v253, v252, v252 quad_perm:[1,0,3,2] row_mask:0xf bank_mask:0xf
	s_and_saveexec_b64 s[20:21], s[4:5]
	ds_add_f32 v251, v253 offset:2080
	s_mov_b64 exec, s[20:21]
